# int8 up GEMM: first K-iteration peeled with srcC=0 MFMAs (drops 128 v_mov accumulator zeroing per unit); K-loops un-rotated so the taken back-edge sits in the load segment
# speedup vs baseline: 1.0123x; 1.0123x over previous
.LBB0_291:
	s_ashr_i32 s21, s20, 31
	s_lshl_b64 s[22:23], s[20:21], 19
	s_add_u32 s22, s46, s22
	s_addc_u32 s23, s47, s23
	s_and_b64 s[24:25], s[40:41], exec
	s_cselect_b32 s21, s23, s29
	s_cselect_b32 s74, s22, s28
	s_ashr_i32 s17, s16, 31
	s_lshl_b64 s[24:25], s[16:17], 19
	s_add_u32 s24, s52, s24
	s_addc_u32 s25, s54, s25
	s_and_b64 s[36:37], s[40:41], exec
	s_cselect_b32 s17, s25, s35
	s_cselect_b32 s75, s24, s34
	s_lshl_b32 s30, s30, 7
	s_ashr_i32 s27, s26, 31
	s_ashr_i32 s31, s30, 31
	s_lshl_b64 s[36:37], s[26:27], 10
	s_add_u32 s27, s55, s36
	v_lshl_add_u64 v[2:3], s[30:31], 2, v[212:213]
	s_addc_u32 s31, s59, s37
	v_mov_b32_e32 v4, s31
	v_cndmask_b32_e64 v3, v3, v4, s[38:39]
	v_mov_b32_e32 v4, s27
	s_add_u32 s36, s28, 0x40080
	v_cndmask_b32_e64 v2, v2, v4, s[38:39]
	s_addc_u32 s37, s29, 0
	v_lshl_add_u64 v[222:223], v[214:215], 2, v[2:3]
	s_add_u32 s27, s34, 0x100
	v_lshl_add_u64 v[224:225], s[36:37], 0, v[218:219]
	v_lshl_add_u64 v[226:227], s[36:37], 0, v[220:221]
	s_addc_u32 s31, s35, 0
	s_mov_b32 s76, -2
	s_mov_b64 s[34:35], 0
	s_branch .LP8_293
.LP8_293:
	v_add_u32_e32 v132, 0, v243
	v_add_u32_e32 v133, 0x10000, v132
	v_add_u32_e32 v144, 0x14000, v132
	ds_read_b128 v[148:151], v133
	ds_read_b128 v[152:155], v133 offset:1024
	ds_read_b128 v[156:159], v133 offset:2048
	ds_read_b128 v[160:163], v133 offset:3072
	ds_read_b128 v[132:135], v144
	ds_read_b128 v[136:139], v144 offset:1024
	ds_read_b128 v[140:143], v144 offset:2048
	ds_read_b128 v[144:147], v144 offset:3072
	v_lshl_add_u64 v[246:247], v[224:225], 0, s[34:35]
	s_add_i32 m0, s63, 0xc000
	ds_read_b128 v[188:191], v244
	ds_read_b128 v[192:195], v244 offset:1024
	ds_read_b128 v[180:183], v244 offset:2048
	ds_read_b128 v[184:187], v244 offset:3072
	ds_read_b128 v[172:175], v244 offset:4096
	ds_read_b128 v[176:179], v244 offset:5120
	ds_read_b128 v[164:167], v244 offset:6144
	ds_read_b128 v[168:171], v244 offset:7168
	global_load_lds_dwordx4 v[246:247], off
	v_lshl_add_u64 v[246:247], v[226:227], 0, s[34:35]
	s_add_i32 m0, s63, 0xe000
	s_cmp_eq_u32 s34, 0
	global_load_lds_dwordx4 v[246:247], off
	s_waitcnt vmcnt(8)
	s_waitcnt lgkmcnt(0)
	s_cselect_b64 s[36:37], -1, 0
	s_and_b64 s[36:37], s[36:37], s[12:13]
	s_andn2_b64 vcc, exec, s[36:37]
	s_add_u32 s36, s28, s34
	s_addc_u32 s37, s29, s35
	s_add_u32 s36, s36, 0x100
	s_addc_u32 s37, s37, 0
	s_add_u32 s77, s27, s34
	s_addc_u32 s78, s31, s35
	s_cmpk_eq_i32 s34, 0x700
	s_cselect_b32 s43, s21, s37
	s_cselect_b32 s42, s74, s36
	s_cselect_b32 s37, s17, s78
	s_cselect_b32 s36, s75, s77
	s_setprio 1
	s_barrier
	s_cbranch_vccz .LP8_rss
.LP8_292:
	v_mfma_i32_16x16x64_i8 v[128:131], v[148:151], v[188:191], 0
	v_mfma_i32_16x16x64_i8 v[128:131], v[152:155], v[192:195], v[128:131]
	v_mfma_i32_16x16x64_i8 v[120:123], v[156:159], v[188:191], 0
	v_mfma_i32_16x16x64_i8 v[120:123], v[160:163], v[192:195], v[120:123]
	v_mfma_i32_16x16x64_i8 v[112:115], v[148:151], v[180:183], 0
	v_mfma_i32_16x16x64_i8 v[112:115], v[152:155], v[184:187], v[112:115]
	v_mfma_i32_16x16x64_i8 v[104:107], v[156:159], v[180:183], 0
	v_mfma_i32_16x16x64_i8 v[104:107], v[160:163], v[184:187], v[104:107]
	v_mfma_i32_16x16x64_i8 v[96:99], v[148:151], v[172:175], 0
	v_mfma_i32_16x16x64_i8 v[96:99], v[152:155], v[176:179], v[96:99]
	v_mfma_i32_16x16x64_i8 v[88:91], v[156:159], v[172:175], 0
	v_mfma_i32_16x16x64_i8 v[88:91], v[160:163], v[176:179], v[88:91]
	v_mfma_i32_16x16x64_i8 v[80:83], v[148:151], v[164:167], 0
	v_mfma_i32_16x16x64_i8 v[80:83], v[152:155], v[168:171], v[80:83]
	v_mfma_i32_16x16x64_i8 v[72:75], v[156:159], v[164:167], 0
	v_mfma_i32_16x16x64_i8 v[72:75], v[160:163], v[168:171], v[72:75]
	v_mfma_i32_16x16x64_i8 v[124:127], v[132:135], v[188:191], 0
	v_mfma_i32_16x16x64_i8 v[124:127], v[136:139], v[192:195], v[124:127]
	v_mfma_i32_16x16x64_i8 v[116:119], v[140:143], v[188:191], 0
	v_mfma_i32_16x16x64_i8 v[116:119], v[144:147], v[192:195], v[116:119]
	v_mfma_i32_16x16x64_i8 v[108:111], v[132:135], v[180:183], 0
	v_mfma_i32_16x16x64_i8 v[108:111], v[136:139], v[184:187], v[108:111]
	v_mfma_i32_16x16x64_i8 v[100:103], v[140:143], v[180:183], 0
	v_mfma_i32_16x16x64_i8 v[100:103], v[144:147], v[184:187], v[100:103]
	v_mfma_i32_16x16x64_i8 v[92:95], v[132:135], v[172:175], 0
	v_mfma_i32_16x16x64_i8 v[92:95], v[136:139], v[176:179], v[92:95]
	v_mfma_i32_16x16x64_i8 v[84:87], v[140:143], v[172:175], 0
	v_mfma_i32_16x16x64_i8 v[84:87], v[144:147], v[176:179], v[84:87]
	v_mfma_i32_16x16x64_i8 v[76:79], v[132:135], v[164:167], 0
	v_mfma_i32_16x16x64_i8 v[76:79], v[136:139], v[168:171], v[76:79]
	v_mfma_i32_16x16x64_i8 v[68:71], v[140:143], v[164:167], 0
	v_mfma_i32_16x16x64_i8 v[68:71], v[144:147], v[168:171], v[68:71]
	s_barrier
	s_setprio 0
	s_mov_b32 m0, s64
	v_lshl_add_u64 v[246:247], s[36:37], 0, v[34:35]
	s_add_u32 vcc_lo, s36, 0x40000
	ds_read_b128 v[164:167], v244 offset:16384
	ds_read_b128 v[168:171], v244 offset:17408
	ds_read_b128 v[172:175], v244 offset:18432
	ds_read_b128 v[176:179], v244 offset:19456
	ds_read_b128 v[180:183], v244 offset:20480
	ds_read_b128 v[184:187], v244 offset:21504
	ds_read_b128 v[188:191], v244 offset:22528
	ds_read_b128 v[192:195], v244 offset:23552
	global_load_lds_dwordx4 v[246:247], off
	v_lshl_add_u64 v[248:249], s[36:37], 0, v[210:211]
	s_mov_b32 m0, s65
	s_addc_u32 vcc_hi, s37, 0
	global_load_lds_dwordx4 v[248:249], off
	v_lshl_add_u64 v[250:251], vcc, 0, v[34:35]
	s_mov_b32 m0, s66
	v_lshl_add_u64 v[198:199], s[42:43], 0, v[208:209]
	global_load_lds_dwordx4 v[250:251], off
	v_lshl_add_u64 v[250:251], vcc, 0, v[210:211]
	s_mov_b32 m0, s67
	s_nop 0
	global_load_lds_dwordx4 v[250:251], off
	v_lshl_add_u64 v[250:251], s[42:43], 0, v[206:207]
	s_mov_b32 m0, s63
	s_nop 0
	global_load_lds_dwordx4 v[250:251], off
	s_mov_b32 m0, s68
	s_nop 0
	global_load_lds_dwordx4 v[198:199], off
	s_waitcnt vmcnt(8)
	s_waitcnt lgkmcnt(0)
	s_setprio 1
	s_barrier
	v_mfma_i32_16x16x64_i8 v[64:67], v[148:151], v[164:167], 0
	v_mfma_i32_16x16x64_i8 v[64:67], v[152:155], v[168:171], v[64:67]
	v_mfma_i32_16x16x64_i8 v[56:59], v[156:159], v[164:167], 0
	v_mfma_i32_16x16x64_i8 v[56:59], v[160:163], v[168:171], v[56:59]
	v_mfma_i32_16x16x64_i8 v[48:51], v[148:151], v[172:175], 0
	v_mfma_i32_16x16x64_i8 v[48:51], v[152:155], v[176:179], v[48:51]
	v_mfma_i32_16x16x64_i8 v[40:43], v[156:159], v[172:175], 0
	v_mfma_i32_16x16x64_i8 v[40:43], v[160:163], v[176:179], v[40:43]
	v_mfma_i32_16x16x64_i8 v[30:33], v[148:151], v[180:183], 0
	v_mfma_i32_16x16x64_i8 v[30:33], v[152:155], v[184:187], v[30:33]
	v_mfma_i32_16x16x64_i8 v[22:25], v[156:159], v[180:183], 0
	v_mfma_i32_16x16x64_i8 v[22:25], v[160:163], v[184:187], v[22:25]
	v_mfma_i32_16x16x64_i8 v[14:17], v[148:151], v[188:191], 0
	v_mfma_i32_16x16x64_i8 v[14:17], v[152:155], v[192:195], v[14:17]
	v_mfma_i32_16x16x64_i8 v[6:9], v[156:159], v[188:191], 0
	v_mfma_i32_16x16x64_i8 v[6:9], v[160:163], v[192:195], v[6:9]
	v_mfma_i32_16x16x64_i8 v[60:63], v[132:135], v[164:167], 0
	v_mfma_i32_16x16x64_i8 v[60:63], v[136:139], v[168:171], v[60:63]
	v_mfma_i32_16x16x64_i8 v[52:55], v[140:143], v[164:167], 0
	v_mfma_i32_16x16x64_i8 v[52:55], v[144:147], v[168:171], v[52:55]
	v_mfma_i32_16x16x64_i8 v[44:47], v[132:135], v[172:175], 0
	v_mfma_i32_16x16x64_i8 v[44:47], v[136:139], v[176:179], v[44:47]
	v_mfma_i32_16x16x64_i8 v[36:39], v[140:143], v[172:175], 0
	v_mfma_i32_16x16x64_i8 v[36:39], v[144:147], v[176:179], v[36:39]
	v_mfma_i32_16x16x64_i8 v[26:29], v[132:135], v[180:183], 0
	v_mfma_i32_16x16x64_i8 v[26:29], v[136:139], v[184:187], v[26:29]
	v_mfma_i32_16x16x64_i8 v[18:21], v[140:143], v[180:183], 0
	v_mfma_i32_16x16x64_i8 v[18:21], v[144:147], v[184:187], v[18:21]
	v_mfma_i32_16x16x64_i8 v[10:13], v[132:135], v[188:191], 0
	v_mfma_i32_16x16x64_i8 v[10:13], v[136:139], v[192:195], v[10:13]
	v_mfma_i32_16x16x64_i8 v[2:5], v[140:143], v[188:191], 0
	v_mfma_i32_16x16x64_i8 v[2:5], v[144:147], v[192:195], v[2:5]
	s_barrier
	s_setprio 0
	s_add_i32 s77, 0, 0x18000
	s_add_i32 s78, 0, 0x1c000
	v_add_u32_e32 v144, s77, v243
	v_add_u32_e32 v160, s78, v243
	ds_read_b128 v[132:135], v144
	ds_read_b128 v[136:139], v144 offset:1024
	ds_read_b128 v[140:143], v144 offset:2048
	ds_read_b128 v[144:147], v144 offset:3072
	ds_read_b128 v[148:151], v160
	ds_read_b128 v[152:155], v160 offset:1024
	ds_read_b128 v[156:159], v160 offset:2048
	ds_read_b128 v[160:163], v160 offset:3072
	s_add_u32 s42, s42, 0x40000
	s_addc_u32 s43, s43, 0
	s_mov_b32 m0, s69
	v_lshl_add_u64 v[200:201], s[42:43], 0, v[206:207]
	ds_read_b128 v[164:167], v244 offset:32768
	ds_read_b128 v[168:171], v244 offset:33792
	ds_read_b128 v[172:175], v244 offset:34816
	ds_read_b128 v[176:179], v244 offset:35840
	ds_read_b128 v[180:183], v244 offset:36864
	ds_read_b128 v[184:187], v244 offset:37888
	ds_read_b128 v[188:191], v244 offset:38912
	ds_read_b128 v[192:195], v244 offset:39936
	global_load_lds_dwordx4 v[200:201], off
	v_lshl_add_u64 v[200:201], s[42:43], 0, v[208:209]
	s_mov_b32 m0, s70
	s_nop 0
	global_load_lds_dwordx4 v[200:201], off
	s_waitcnt vmcnt(8)
	s_waitcnt lgkmcnt(0)
	s_setprio 1
	s_barrier
	v_mfma_i32_16x16x64_i8 v[128:131], v[132:135], v[164:167], v[128:131]
	v_mfma_i32_16x16x64_i8 v[128:131], v[136:139], v[168:171], v[128:131]
	v_mfma_i32_16x16x64_i8 v[120:123], v[140:143], v[164:167], v[120:123]
	v_mfma_i32_16x16x64_i8 v[120:123], v[144:147], v[168:171], v[120:123]
	v_mfma_i32_16x16x64_i8 v[112:115], v[132:135], v[172:175], v[112:115]
	v_mfma_i32_16x16x64_i8 v[112:115], v[136:139], v[176:179], v[112:115]
	v_mfma_i32_16x16x64_i8 v[104:107], v[140:143], v[172:175], v[104:107]
	v_mfma_i32_16x16x64_i8 v[104:107], v[144:147], v[176:179], v[104:107]
	v_mfma_i32_16x16x64_i8 v[96:99], v[132:135], v[180:183], v[96:99]
	v_mfma_i32_16x16x64_i8 v[96:99], v[136:139], v[184:187], v[96:99]
	v_mfma_i32_16x16x64_i8 v[88:91], v[140:143], v[180:183], v[88:91]
	v_mfma_i32_16x16x64_i8 v[88:91], v[144:147], v[184:187], v[88:91]
	v_mfma_i32_16x16x64_i8 v[80:83], v[132:135], v[188:191], v[80:83]
	v_mfma_i32_16x16x64_i8 v[80:83], v[136:139], v[192:195], v[80:83]
	v_mfma_i32_16x16x64_i8 v[72:75], v[140:143], v[188:191], v[72:75]
	v_mfma_i32_16x16x64_i8 v[72:75], v[144:147], v[192:195], v[72:75]
	v_mfma_i32_16x16x64_i8 v[124:127], v[148:151], v[164:167], v[124:127]
	v_mfma_i32_16x16x64_i8 v[124:127], v[152:155], v[168:171], v[124:127]
	v_mfma_i32_16x16x64_i8 v[116:119], v[156:159], v[164:167], v[116:119]
	v_mfma_i32_16x16x64_i8 v[116:119], v[160:163], v[168:171], v[116:119]
	v_mfma_i32_16x16x64_i8 v[108:111], v[148:151], v[172:175], v[108:111]
	v_mfma_i32_16x16x64_i8 v[108:111], v[152:155], v[176:179], v[108:111]
	v_mfma_i32_16x16x64_i8 v[100:103], v[156:159], v[172:175], v[100:103]
	v_mfma_i32_16x16x64_i8 v[100:103], v[160:163], v[176:179], v[100:103]
	v_mfma_i32_16x16x64_i8 v[92:95], v[148:151], v[180:183], v[92:95]
	v_mfma_i32_16x16x64_i8 v[92:95], v[152:155], v[184:187], v[92:95]
	v_mfma_i32_16x16x64_i8 v[84:87], v[156:159], v[180:183], v[84:87]
	v_mfma_i32_16x16x64_i8 v[84:87], v[160:163], v[184:187], v[84:87]
	v_mfma_i32_16x16x64_i8 v[76:79], v[148:151], v[188:191], v[76:79]
	v_mfma_i32_16x16x64_i8 v[76:79], v[152:155], v[192:195], v[76:79]
	v_mfma_i32_16x16x64_i8 v[68:71], v[156:159], v[188:191], v[68:71]
	v_mfma_i32_16x16x64_i8 v[68:71], v[160:163], v[192:195], v[68:71]
	s_barrier
	s_setprio 0
	s_add_i32 s42, s77, s62
	v_lshl_add_u64 v[200:201], v[246:247], 0, s[18:19]
	s_mov_b32 m0, s42
	ds_read_b128 v[164:167], v244 offset:49152
	ds_read_b128 v[168:171], v244 offset:50176
	ds_read_b128 v[172:175], v244 offset:51200
	ds_read_b128 v[176:179], v244 offset:52224
	ds_read_b128 v[180:183], v244 offset:53248
	ds_read_b128 v[184:187], v244 offset:54272
	ds_read_b128 v[188:191], v244 offset:55296
	ds_read_b128 v[192:195], v244 offset:56320
	global_load_lds_dwordx4 v[200:201], off
	s_add_i32 m0, s42, 0x2000
	s_add_u32 s36, s36, 0x40080
	v_lshl_add_u64 v[200:201], v[248:249], 0, s[18:19]
	s_addc_u32 s37, s37, 0
	s_add_i32 s42, s78, s62
	global_load_lds_dwordx4 v[200:201], off
	v_lshl_add_u64 v[200:201], s[36:37], 0, v[34:35]
	s_mov_b32 m0, s42
	v_lshl_add_u64 v[198:199], v[198:199], 0, s[18:19]
	global_load_lds_dwordx4 v[200:201], off
	v_lshl_add_u64 v[200:201], s[36:37], 0, v[210:211]
	s_add_i32 m0, s42, 0x2000
	s_nop 0
	global_load_lds_dwordx4 v[200:201], off
	v_lshl_add_u64 v[200:201], v[250:251], 0, s[18:19]
	s_mov_b32 m0, s71
	s_nop 0
	global_load_lds_dwordx4 v[200:201], off
	s_mov_b32 m0, s72
	s_nop 0
	global_load_lds_dwordx4 v[198:199], off
	s_waitcnt vmcnt(8)
	s_waitcnt lgkmcnt(0)
	s_setprio 1
	s_barrier
	v_mfma_i32_16x16x64_i8 v[64:67], v[132:135], v[164:167], v[64:67]
	v_mfma_i32_16x16x64_i8 v[64:67], v[136:139], v[168:171], v[64:67]
	v_mfma_i32_16x16x64_i8 v[56:59], v[140:143], v[164:167], v[56:59]
	v_mfma_i32_16x16x64_i8 v[56:59], v[144:147], v[168:171], v[56:59]
	v_mfma_i32_16x16x64_i8 v[48:51], v[132:135], v[172:175], v[48:51]
	v_mfma_i32_16x16x64_i8 v[48:51], v[136:139], v[176:179], v[48:51]
	v_mfma_i32_16x16x64_i8 v[40:43], v[140:143], v[172:175], v[40:43]
	v_mfma_i32_16x16x64_i8 v[40:43], v[144:147], v[176:179], v[40:43]
	v_mfma_i32_16x16x64_i8 v[30:33], v[132:135], v[180:183], v[30:33]
	v_mfma_i32_16x16x64_i8 v[30:33], v[136:139], v[184:187], v[30:33]
	v_mfma_i32_16x16x64_i8 v[22:25], v[140:143], v[180:183], v[22:25]
	v_mfma_i32_16x16x64_i8 v[22:25], v[144:147], v[184:187], v[22:25]
	v_mfma_i32_16x16x64_i8 v[14:17], v[132:135], v[188:191], v[14:17]
	v_mfma_i32_16x16x64_i8 v[14:17], v[136:139], v[192:195], v[14:17]
	v_mfma_i32_16x16x64_i8 v[6:9], v[140:143], v[188:191], v[6:9]
	v_mfma_i32_16x16x64_i8 v[6:9], v[144:147], v[192:195], v[6:9]
	v_mfma_i32_16x16x64_i8 v[60:63], v[148:151], v[164:167], v[60:63]
	v_mfma_i32_16x16x64_i8 v[60:63], v[152:155], v[168:171], v[60:63]
	v_mfma_i32_16x16x64_i8 v[52:55], v[156:159], v[164:167], v[52:55]
	v_mfma_i32_16x16x64_i8 v[52:55], v[160:163], v[168:171], v[52:55]
	v_mfma_i32_16x16x64_i8 v[44:47], v[148:151], v[172:175], v[44:47]
	v_mfma_i32_16x16x64_i8 v[44:47], v[152:155], v[176:179], v[44:47]
	v_mfma_i32_16x16x64_i8 v[36:39], v[156:159], v[172:175], v[36:39]
	v_mfma_i32_16x16x64_i8 v[36:39], v[160:163], v[176:179], v[36:39]
	v_mfma_i32_16x16x64_i8 v[26:29], v[148:151], v[180:183], v[26:29]
	v_mfma_i32_16x16x64_i8 v[26:29], v[152:155], v[184:187], v[26:29]
	v_mfma_i32_16x16x64_i8 v[18:21], v[156:159], v[180:183], v[18:21]
	v_mfma_i32_16x16x64_i8 v[18:21], v[160:163], v[184:187], v[18:21]
	v_mfma_i32_16x16x64_i8 v[10:13], v[148:151], v[188:191], v[10:13]
	v_mfma_i32_16x16x64_i8 v[10:13], v[152:155], v[192:195], v[10:13]
	v_mfma_i32_16x16x64_i8 v[2:5], v[156:159], v[188:191], v[2:5]
	v_mfma_i32_16x16x64_i8 v[2:5], v[160:163], v[192:195], v[2:5]
	s_barrier
	s_setprio 0
	s_add_i32 s76, s76, 2
	s_add_u32 s34, s34, 0x100
	s_addc_u32 s35, s35, 0
	s_cmp_gt_u32 s76, 13
	s_cbranch_scc0 .LBB0_293
	s_branch .LBB0_295
.LP8_rss:
	s_add_i32 m0, s63, 0x21200
	s_nop 0
	global_load_lds_dwordx4 v[222:223], off
	s_branch .LP8_292

.LBB0_292:
	v_mfma_i32_16x16x64_i8 v[128:131], v[148:151], v[188:191], v[128:131]
	v_mfma_i32_16x16x64_i8 v[128:131], v[152:155], v[192:195], v[128:131]
	v_mfma_i32_16x16x64_i8 v[120:123], v[156:159], v[188:191], v[120:123]
	v_mfma_i32_16x16x64_i8 v[120:123], v[160:163], v[192:195], v[120:123]
	v_mfma_i32_16x16x64_i8 v[112:115], v[148:151], v[180:183], v[112:115]
	v_mfma_i32_16x16x64_i8 v[112:115], v[152:155], v[184:187], v[112:115]
	v_mfma_i32_16x16x64_i8 v[104:107], v[156:159], v[180:183], v[104:107]
	v_mfma_i32_16x16x64_i8 v[104:107], v[160:163], v[184:187], v[104:107]
	v_mfma_i32_16x16x64_i8 v[96:99], v[148:151], v[172:175], v[96:99]
	v_mfma_i32_16x16x64_i8 v[96:99], v[152:155], v[176:179], v[96:99]
	v_mfma_i32_16x16x64_i8 v[88:91], v[156:159], v[172:175], v[88:91]
	v_mfma_i32_16x16x64_i8 v[88:91], v[160:163], v[176:179], v[88:91]
	v_mfma_i32_16x16x64_i8 v[80:83], v[148:151], v[164:167], v[80:83]
	v_mfma_i32_16x16x64_i8 v[80:83], v[152:155], v[168:171], v[80:83]
	v_mfma_i32_16x16x64_i8 v[72:75], v[156:159], v[164:167], v[72:75]
	v_mfma_i32_16x16x64_i8 v[72:75], v[160:163], v[168:171], v[72:75]
	v_mfma_i32_16x16x64_i8 v[124:127], v[132:135], v[188:191], v[124:127]
	v_mfma_i32_16x16x64_i8 v[124:127], v[136:139], v[192:195], v[124:127]
	v_mfma_i32_16x16x64_i8 v[116:119], v[140:143], v[188:191], v[116:119]
	v_mfma_i32_16x16x64_i8 v[116:119], v[144:147], v[192:195], v[116:119]
	v_mfma_i32_16x16x64_i8 v[108:111], v[132:135], v[180:183], v[108:111]
	v_mfma_i32_16x16x64_i8 v[108:111], v[136:139], v[184:187], v[108:111]
	v_mfma_i32_16x16x64_i8 v[100:103], v[140:143], v[180:183], v[100:103]
	v_mfma_i32_16x16x64_i8 v[100:103], v[144:147], v[184:187], v[100:103]
	v_mfma_i32_16x16x64_i8 v[92:95], v[132:135], v[172:175], v[92:95]
	v_mfma_i32_16x16x64_i8 v[92:95], v[136:139], v[176:179], v[92:95]
	v_mfma_i32_16x16x64_i8 v[84:87], v[140:143], v[172:175], v[84:87]
	v_mfma_i32_16x16x64_i8 v[84:87], v[144:147], v[176:179], v[84:87]
	v_mfma_i32_16x16x64_i8 v[76:79], v[132:135], v[164:167], v[76:79]
	v_mfma_i32_16x16x64_i8 v[76:79], v[136:139], v[168:171], v[76:79]
	v_mfma_i32_16x16x64_i8 v[68:71], v[140:143], v[164:167], v[68:71]
	v_mfma_i32_16x16x64_i8 v[68:71], v[144:147], v[168:171], v[68:71]
	s_barrier
	s_setprio 0
	s_mov_b32 m0, s64
	v_lshl_add_u64 v[246:247], s[36:37], 0, v[34:35]
	s_add_u32 vcc_lo, s36, 0x40000
	ds_read_b128 v[164:167], v244 offset:16384
	ds_read_b128 v[168:171], v244 offset:17408
	ds_read_b128 v[172:175], v244 offset:18432
	ds_read_b128 v[176:179], v244 offset:19456
	ds_read_b128 v[180:183], v244 offset:20480
	ds_read_b128 v[184:187], v244 offset:21504
	ds_read_b128 v[188:191], v244 offset:22528
	ds_read_b128 v[192:195], v244 offset:23552
	global_load_lds_dwordx4 v[246:247], off
	v_lshl_add_u64 v[248:249], s[36:37], 0, v[210:211]
	s_mov_b32 m0, s65
	s_addc_u32 vcc_hi, s37, 0
	global_load_lds_dwordx4 v[248:249], off
	v_lshl_add_u64 v[250:251], vcc, 0, v[34:35]
	s_mov_b32 m0, s66
	v_lshl_add_u64 v[198:199], s[42:43], 0, v[208:209]
	global_load_lds_dwordx4 v[250:251], off
	v_lshl_add_u64 v[250:251], vcc, 0, v[210:211]
	s_mov_b32 m0, s67
	s_nop 0
	global_load_lds_dwordx4 v[250:251], off
	v_lshl_add_u64 v[250:251], s[42:43], 0, v[206:207]
	s_mov_b32 m0, s63
	s_nop 0
	global_load_lds_dwordx4 v[250:251], off
	s_mov_b32 m0, s68
	s_nop 0
	global_load_lds_dwordx4 v[198:199], off
	s_waitcnt vmcnt(8)
	s_waitcnt lgkmcnt(0)
	s_setprio 1
	s_barrier
	v_mfma_i32_16x16x64_i8 v[64:67], v[148:151], v[164:167], v[64:67]
	v_mfma_i32_16x16x64_i8 v[64:67], v[152:155], v[168:171], v[64:67]
	v_mfma_i32_16x16x64_i8 v[56:59], v[156:159], v[164:167], v[56:59]
	v_mfma_i32_16x16x64_i8 v[56:59], v[160:163], v[168:171], v[56:59]
	v_mfma_i32_16x16x64_i8 v[48:51], v[148:151], v[172:175], v[48:51]
	v_mfma_i32_16x16x64_i8 v[48:51], v[152:155], v[176:179], v[48:51]
	v_mfma_i32_16x16x64_i8 v[40:43], v[156:159], v[172:175], v[40:43]
	v_mfma_i32_16x16x64_i8 v[40:43], v[160:163], v[176:179], v[40:43]
	v_mfma_i32_16x16x64_i8 v[30:33], v[148:151], v[180:183], v[30:33]
	v_mfma_i32_16x16x64_i8 v[30:33], v[152:155], v[184:187], v[30:33]
	v_mfma_i32_16x16x64_i8 v[22:25], v[156:159], v[180:183], v[22:25]
	v_mfma_i32_16x16x64_i8 v[22:25], v[160:163], v[184:187], v[22:25]
	v_mfma_i32_16x16x64_i8 v[14:17], v[148:151], v[188:191], v[14:17]
	v_mfma_i32_16x16x64_i8 v[14:17], v[152:155], v[192:195], v[14:17]
	v_mfma_i32_16x16x64_i8 v[6:9], v[156:159], v[188:191], v[6:9]
	v_mfma_i32_16x16x64_i8 v[6:9], v[160:163], v[192:195], v[6:9]
	v_mfma_i32_16x16x64_i8 v[60:63], v[132:135], v[164:167], v[60:63]
	v_mfma_i32_16x16x64_i8 v[60:63], v[136:139], v[168:171], v[60:63]
	v_mfma_i32_16x16x64_i8 v[52:55], v[140:143], v[164:167], v[52:55]
	v_mfma_i32_16x16x64_i8 v[52:55], v[144:147], v[168:171], v[52:55]
	v_mfma_i32_16x16x64_i8 v[44:47], v[132:135], v[172:175], v[44:47]
	v_mfma_i32_16x16x64_i8 v[44:47], v[136:139], v[176:179], v[44:47]
	v_mfma_i32_16x16x64_i8 v[36:39], v[140:143], v[172:175], v[36:39]
	v_mfma_i32_16x16x64_i8 v[36:39], v[144:147], v[176:179], v[36:39]
	v_mfma_i32_16x16x64_i8 v[26:29], v[132:135], v[180:183], v[26:29]
	v_mfma_i32_16x16x64_i8 v[26:29], v[136:139], v[184:187], v[26:29]
	v_mfma_i32_16x16x64_i8 v[18:21], v[140:143], v[180:183], v[18:21]
	v_mfma_i32_16x16x64_i8 v[18:21], v[144:147], v[184:187], v[18:21]
	v_mfma_i32_16x16x64_i8 v[10:13], v[132:135], v[188:191], v[10:13]
	v_mfma_i32_16x16x64_i8 v[10:13], v[136:139], v[192:195], v[10:13]
	v_mfma_i32_16x16x64_i8 v[2:5], v[140:143], v[188:191], v[2:5]
	v_mfma_i32_16x16x64_i8 v[2:5], v[144:147], v[192:195], v[2:5]
	s_barrier
	s_setprio 0
	s_add_i32 s77, 0, 0x18000
	s_add_i32 s78, 0, 0x1c000
	v_add_u32_e32 v144, s77, v243
	v_add_u32_e32 v160, s78, v243
	ds_read_b128 v[132:135], v144
	ds_read_b128 v[136:139], v144 offset:1024
	ds_read_b128 v[140:143], v144 offset:2048
	ds_read_b128 v[144:147], v144 offset:3072
	ds_read_b128 v[148:151], v160
	ds_read_b128 v[152:155], v160 offset:1024
	ds_read_b128 v[156:159], v160 offset:2048
	ds_read_b128 v[160:163], v160 offset:3072
	s_add_u32 s42, s42, 0x40000
	s_addc_u32 s43, s43, 0
	s_mov_b32 m0, s69
	v_lshl_add_u64 v[200:201], s[42:43], 0, v[206:207]
	ds_read_b128 v[164:167], v244 offset:32768
	ds_read_b128 v[168:171], v244 offset:33792
	ds_read_b128 v[172:175], v244 offset:34816
	ds_read_b128 v[176:179], v244 offset:35840
	ds_read_b128 v[180:183], v244 offset:36864
	ds_read_b128 v[184:187], v244 offset:37888
	ds_read_b128 v[188:191], v244 offset:38912
	ds_read_b128 v[192:195], v244 offset:39936
	global_load_lds_dwordx4 v[200:201], off
	v_lshl_add_u64 v[200:201], s[42:43], 0, v[208:209]
	s_mov_b32 m0, s70
	s_nop 0
	global_load_lds_dwordx4 v[200:201], off
	s_waitcnt vmcnt(8)
	s_waitcnt lgkmcnt(0)
	s_setprio 1
	s_barrier
	v_mfma_i32_16x16x64_i8 v[128:131], v[132:135], v[164:167], v[128:131]
	v_mfma_i32_16x16x64_i8 v[128:131], v[136:139], v[168:171], v[128:131]
	v_mfma_i32_16x16x64_i8 v[120:123], v[140:143], v[164:167], v[120:123]
	v_mfma_i32_16x16x64_i8 v[120:123], v[144:147], v[168:171], v[120:123]
	v_mfma_i32_16x16x64_i8 v[112:115], v[132:135], v[172:175], v[112:115]
	v_mfma_i32_16x16x64_i8 v[112:115], v[136:139], v[176:179], v[112:115]
	v_mfma_i32_16x16x64_i8 v[104:107], v[140:143], v[172:175], v[104:107]
	v_mfma_i32_16x16x64_i8 v[104:107], v[144:147], v[176:179], v[104:107]
	v_mfma_i32_16x16x64_i8 v[96:99], v[132:135], v[180:183], v[96:99]
	v_mfma_i32_16x16x64_i8 v[96:99], v[136:139], v[184:187], v[96:99]
	v_mfma_i32_16x16x64_i8 v[88:91], v[140:143], v[180:183], v[88:91]
	v_mfma_i32_16x16x64_i8 v[88:91], v[144:147], v[184:187], v[88:91]
	v_mfma_i32_16x16x64_i8 v[80:83], v[132:135], v[188:191], v[80:83]
	v_mfma_i32_16x16x64_i8 v[80:83], v[136:139], v[192:195], v[80:83]
	v_mfma_i32_16x16x64_i8 v[72:75], v[140:143], v[188:191], v[72:75]
	v_mfma_i32_16x16x64_i8 v[72:75], v[144:147], v[192:195], v[72:75]
	v_mfma_i32_16x16x64_i8 v[124:127], v[148:151], v[164:167], v[124:127]
	v_mfma_i32_16x16x64_i8 v[124:127], v[152:155], v[168:171], v[124:127]
	v_mfma_i32_16x16x64_i8 v[116:119], v[156:159], v[164:167], v[116:119]
	v_mfma_i32_16x16x64_i8 v[116:119], v[160:163], v[168:171], v[116:119]
	v_mfma_i32_16x16x64_i8 v[108:111], v[148:151], v[172:175], v[108:111]
	v_mfma_i32_16x16x64_i8 v[108:111], v[152:155], v[176:179], v[108:111]
	v_mfma_i32_16x16x64_i8 v[100:103], v[156:159], v[172:175], v[100:103]
	v_mfma_i32_16x16x64_i8 v[100:103], v[160:163], v[176:179], v[100:103]
	v_mfma_i32_16x16x64_i8 v[92:95], v[148:151], v[180:183], v[92:95]
	v_mfma_i32_16x16x64_i8 v[92:95], v[152:155], v[184:187], v[92:95]
	v_mfma_i32_16x16x64_i8 v[84:87], v[156:159], v[180:183], v[84:87]
	v_mfma_i32_16x16x64_i8 v[84:87], v[160:163], v[184:187], v[84:87]
	v_mfma_i32_16x16x64_i8 v[76:79], v[148:151], v[188:191], v[76:79]
	v_mfma_i32_16x16x64_i8 v[76:79], v[152:155], v[192:195], v[76:79]
	v_mfma_i32_16x16x64_i8 v[68:71], v[156:159], v[188:191], v[68:71]
	v_mfma_i32_16x16x64_i8 v[68:71], v[160:163], v[192:195], v[68:71]
	s_barrier
	s_setprio 0
	s_add_i32 s42, s77, s62
	v_lshl_add_u64 v[200:201], v[246:247], 0, s[18:19]
	s_mov_b32 m0, s42
	ds_read_b128 v[164:167], v244 offset:49152
	ds_read_b128 v[168:171], v244 offset:50176
	ds_read_b128 v[172:175], v244 offset:51200
	ds_read_b128 v[176:179], v244 offset:52224
	ds_read_b128 v[180:183], v244 offset:53248
	ds_read_b128 v[184:187], v244 offset:54272
	ds_read_b128 v[188:191], v244 offset:55296
	ds_read_b128 v[192:195], v244 offset:56320
	global_load_lds_dwordx4 v[200:201], off
	s_add_i32 m0, s42, 0x2000
	s_add_u32 s36, s36, 0x40080
	v_lshl_add_u64 v[200:201], v[248:249], 0, s[18:19]
	s_addc_u32 s37, s37, 0
	s_add_i32 s42, s78, s62
	global_load_lds_dwordx4 v[200:201], off
	v_lshl_add_u64 v[200:201], s[36:37], 0, v[34:35]
	s_mov_b32 m0, s42
	v_lshl_add_u64 v[198:199], v[198:199], 0, s[18:19]
	global_load_lds_dwordx4 v[200:201], off
	v_lshl_add_u64 v[200:201], s[36:37], 0, v[210:211]
	s_add_i32 m0, s42, 0x2000
	s_nop 0
	global_load_lds_dwordx4 v[200:201], off
	v_lshl_add_u64 v[200:201], v[250:251], 0, s[18:19]
	s_mov_b32 m0, s71
	s_nop 0
	global_load_lds_dwordx4 v[200:201], off
	s_mov_b32 m0, s72
	s_nop 0
	global_load_lds_dwordx4 v[198:199], off
	s_waitcnt vmcnt(8)
	s_waitcnt lgkmcnt(0)
	s_setprio 1
	s_barrier
	v_mfma_i32_16x16x64_i8 v[64:67], v[132:135], v[164:167], v[64:67]
	v_mfma_i32_16x16x64_i8 v[64:67], v[136:139], v[168:171], v[64:67]
	v_mfma_i32_16x16x64_i8 v[56:59], v[140:143], v[164:167], v[56:59]
	v_mfma_i32_16x16x64_i8 v[56:59], v[144:147], v[168:171], v[56:59]
	v_mfma_i32_16x16x64_i8 v[48:51], v[132:135], v[172:175], v[48:51]
	v_mfma_i32_16x16x64_i8 v[48:51], v[136:139], v[176:179], v[48:51]
	v_mfma_i32_16x16x64_i8 v[40:43], v[140:143], v[172:175], v[40:43]
	v_mfma_i32_16x16x64_i8 v[40:43], v[144:147], v[176:179], v[40:43]
	v_mfma_i32_16x16x64_i8 v[30:33], v[132:135], v[180:183], v[30:33]
	v_mfma_i32_16x16x64_i8 v[30:33], v[136:139], v[184:187], v[30:33]
	v_mfma_i32_16x16x64_i8 v[22:25], v[140:143], v[180:183], v[22:25]
	v_mfma_i32_16x16x64_i8 v[22:25], v[144:147], v[184:187], v[22:25]
	v_mfma_i32_16x16x64_i8 v[14:17], v[132:135], v[188:191], v[14:17]
	v_mfma_i32_16x16x64_i8 v[14:17], v[136:139], v[192:195], v[14:17]
	v_mfma_i32_16x16x64_i8 v[6:9], v[140:143], v[188:191], v[6:9]
	v_mfma_i32_16x16x64_i8 v[6:9], v[144:147], v[192:195], v[6:9]
	v_mfma_i32_16x16x64_i8 v[60:63], v[148:151], v[164:167], v[60:63]
	v_mfma_i32_16x16x64_i8 v[60:63], v[152:155], v[168:171], v[60:63]
	v_mfma_i32_16x16x64_i8 v[52:55], v[156:159], v[164:167], v[52:55]
	v_mfma_i32_16x16x64_i8 v[52:55], v[160:163], v[168:171], v[52:55]
	v_mfma_i32_16x16x64_i8 v[44:47], v[148:151], v[172:175], v[44:47]
	v_mfma_i32_16x16x64_i8 v[44:47], v[152:155], v[176:179], v[44:47]
	v_mfma_i32_16x16x64_i8 v[36:39], v[156:159], v[172:175], v[36:39]
	v_mfma_i32_16x16x64_i8 v[36:39], v[160:163], v[176:179], v[36:39]
	v_mfma_i32_16x16x64_i8 v[26:29], v[148:151], v[180:183], v[26:29]
	v_mfma_i32_16x16x64_i8 v[26:29], v[152:155], v[184:187], v[26:29]
	v_mfma_i32_16x16x64_i8 v[18:21], v[156:159], v[180:183], v[18:21]
	v_mfma_i32_16x16x64_i8 v[18:21], v[160:163], v[184:187], v[18:21]
	v_mfma_i32_16x16x64_i8 v[10:13], v[148:151], v[188:191], v[10:13]
	v_mfma_i32_16x16x64_i8 v[10:13], v[152:155], v[192:195], v[10:13]
	v_mfma_i32_16x16x64_i8 v[2:5], v[156:159], v[188:191], v[2:5]
	v_mfma_i32_16x16x64_i8 v[2:5], v[160:163], v[192:195], v[2:5]
	s_barrier
	s_setprio 0
	s_add_i32 s76, s76, 2
	s_add_u32 s34, s34, 0x100
	s_addc_u32 s35, s35, 0
	s_cmp_gt_u32 s76, 13
	s_cbranch_scc0 .LBB0_293
	s_branch .LBB0_295

.LBB0_808:
	v_add_u32_e32 v34, 0, v227
	v_add_u32_e32 v132, 0x10000, v34
	v_add_u32_e32 v34, 0x14000, v34
	ds_read_b128 v[148:151], v132
	ds_read_b128 v[152:155], v132 offset:1024
	ds_read_b128 v[156:159], v132 offset:2048
	ds_read_b128 v[160:163], v132 offset:3072
	ds_read_b128 v[132:135], v34
	ds_read_b128 v[136:139], v34 offset:1024
	ds_read_b128 v[140:143], v34 offset:2048
	ds_read_b128 v[144:147], v34 offset:3072
	v_lshl_add_u64 v[198:199], v[222:223], 0, s[34:35]
	s_add_i32 m0, s47, 0xc000
	ds_read_b128 v[188:191], v240
	ds_read_b128 v[192:195], v240 offset:1024
	ds_read_b128 v[180:183], v240 offset:2048
	ds_read_b128 v[184:187], v240 offset:3072
	ds_read_b128 v[172:175], v240 offset:4096
	ds_read_b128 v[176:179], v240 offset:5120
	ds_read_b128 v[164:167], v240 offset:6144
	ds_read_b128 v[168:171], v240 offset:7168
	global_load_lds_dwordx4 v[198:199], off
	v_lshl_add_u64 v[198:199], v[224:225], 0, s[34:35]
	s_add_i32 m0, s47, 0xe000
	s_cmp_lg_u32 s34, 0
	global_load_lds_dwordx4 v[198:199], off
	s_waitcnt vmcnt(8)
	s_waitcnt lgkmcnt(0)
	s_add_u32 s36, s30, s34
	s_addc_u32 s37, s31, s35
	s_add_u32 s36, s36, 0x100
	s_addc_u32 s37, s37, 0
	s_add_u32 s69, s29, s34
	s_addc_u32 s70, s67, s35
	s_cmpk_eq_i32 s34, 0xf00
	s_cselect_b32 s43, s21, s37
	s_cselect_b32 s42, s27, s36
	s_cselect_b32 s37, s17, s70
	s_cselect_b32 s36, s66, s69
	s_cmp_lg_u32 s34, 0
	s_setprio 1
	s_barrier
	s_cbranch_scc0 .Lrss_win
.LBB0_807:
	v_mfma_f32_16x16x32_bf16 v[128:131], v[148:151], v[188:191], v[128:131]
	v_mfma_f32_16x16x32_bf16 v[128:131], v[152:155], v[192:195], v[128:131]
	v_mfma_f32_16x16x32_bf16 v[124:127], v[156:159], v[188:191], v[124:127]
	v_mfma_f32_16x16x32_bf16 v[124:127], v[160:163], v[192:195], v[124:127]
	v_mfma_f32_16x16x32_bf16 v[112:115], v[148:151], v[180:183], v[112:115]
	v_mfma_f32_16x16x32_bf16 v[112:115], v[152:155], v[184:187], v[112:115]
	v_mfma_f32_16x16x32_bf16 v[108:111], v[156:159], v[180:183], v[108:111]
	v_mfma_f32_16x16x32_bf16 v[108:111], v[160:163], v[184:187], v[108:111]
	v_mfma_f32_16x16x32_bf16 v[96:99], v[148:151], v[172:175], v[96:99]
	v_mfma_f32_16x16x32_bf16 v[96:99], v[152:155], v[176:179], v[96:99]
	v_mfma_f32_16x16x32_bf16 v[92:95], v[156:159], v[172:175], v[92:95]
	v_mfma_f32_16x16x32_bf16 v[92:95], v[160:163], v[176:179], v[92:95]
	v_mfma_f32_16x16x32_bf16 v[80:83], v[148:151], v[164:167], v[80:83]
	v_mfma_f32_16x16x32_bf16 v[80:83], v[152:155], v[168:171], v[80:83]
	v_mfma_f32_16x16x32_bf16 v[76:79], v[156:159], v[164:167], v[76:79]
	v_mfma_f32_16x16x32_bf16 v[76:79], v[160:163], v[168:171], v[76:79]
	v_mfma_f32_16x16x32_bf16 v[120:123], v[132:135], v[188:191], v[120:123]
	v_mfma_f32_16x16x32_bf16 v[120:123], v[136:139], v[192:195], v[120:123]
	v_mfma_f32_16x16x32_bf16 v[116:119], v[140:143], v[188:191], v[116:119]
	v_mfma_f32_16x16x32_bf16 v[116:119], v[144:147], v[192:195], v[116:119]
	v_mfma_f32_16x16x32_bf16 v[104:107], v[132:135], v[180:183], v[104:107]
	v_mfma_f32_16x16x32_bf16 v[104:107], v[136:139], v[184:187], v[104:107]
	v_mfma_f32_16x16x32_bf16 v[100:103], v[140:143], v[180:183], v[100:103]
	v_mfma_f32_16x16x32_bf16 v[100:103], v[144:147], v[184:187], v[100:103]
	v_mfma_f32_16x16x32_bf16 v[88:91], v[132:135], v[172:175], v[88:91]
	v_mfma_f32_16x16x32_bf16 v[88:91], v[136:139], v[176:179], v[88:91]
	v_mfma_f32_16x16x32_bf16 v[84:87], v[140:143], v[172:175], v[84:87]
	v_mfma_f32_16x16x32_bf16 v[84:87], v[144:147], v[176:179], v[84:87]
	v_mfma_f32_16x16x32_bf16 v[72:75], v[132:135], v[164:167], v[72:75]
	v_mfma_f32_16x16x32_bf16 v[72:75], v[136:139], v[168:171], v[72:75]
	v_mfma_f32_16x16x32_bf16 v[68:71], v[140:143], v[164:167], v[68:71]
	v_mfma_f32_16x16x32_bf16 v[68:71], v[144:147], v[168:171], v[68:71]
	s_barrier
	s_setprio 0
	s_mov_b32 m0, s52
	v_lshl_add_u64 v[198:199], s[36:37], 0, v[208:209]
	s_add_u32 s70, s36, 0x80000
	ds_read_b128 v[164:167], v240 offset:16384
	ds_read_b128 v[168:171], v240 offset:17408
	ds_read_b128 v[172:175], v240 offset:18432
	ds_read_b128 v[176:179], v240 offset:19456
	ds_read_b128 v[180:183], v240 offset:20480
	ds_read_b128 v[184:187], v240 offset:21504
	ds_read_b128 v[188:191], v240 offset:22528
	ds_read_b128 v[192:195], v240 offset:23552
	global_load_lds_dwordx4 v[198:199], off
	v_lshl_add_u64 v[200:201], s[36:37], 0, v[212:213]
	s_mov_b32 m0, s54
	s_addc_u32 s71, s37, 0
	global_load_lds_dwordx4 v[200:201], off
	v_lshl_add_u64 v[242:243], s[70:71], 0, v[208:209]
	s_mov_b32 m0, s55
	v_lshl_add_u64 v[244:245], s[42:43], 0, v[210:211]
	global_load_lds_dwordx4 v[242:243], off
	v_lshl_add_u64 v[242:243], s[70:71], 0, v[212:213]
	s_mov_b32 m0, s59
	s_nop 0
	global_load_lds_dwordx4 v[242:243], off
	v_lshl_add_u64 v[242:243], s[42:43], 0, v[206:207]
	s_mov_b32 m0, s47
	s_nop 0
	global_load_lds_dwordx4 v[242:243], off
	s_mov_b32 m0, s60
	s_nop 0
	global_load_lds_dwordx4 v[244:245], off
	s_waitcnt vmcnt(8)
	s_waitcnt lgkmcnt(0)
	s_setprio 1
	s_barrier
	v_mfma_f32_16x16x32_bf16 v[64:67], v[148:151], v[164:167], v[64:67]
	v_mfma_f32_16x16x32_bf16 v[64:67], v[152:155], v[168:171], v[64:67]
	v_mfma_f32_16x16x32_bf16 v[60:63], v[156:159], v[164:167], v[60:63]
	v_mfma_f32_16x16x32_bf16 v[60:63], v[160:163], v[168:171], v[60:63]
	v_mfma_f32_16x16x32_bf16 v[48:51], v[148:151], v[172:175], v[48:51]
	v_mfma_f32_16x16x32_bf16 v[48:51], v[152:155], v[176:179], v[48:51]
	v_mfma_f32_16x16x32_bf16 v[44:47], v[156:159], v[172:175], v[44:47]
	v_mfma_f32_16x16x32_bf16 v[44:47], v[160:163], v[176:179], v[44:47]
	v_mfma_f32_16x16x32_bf16 v[30:33], v[148:151], v[180:183], v[30:33]
	v_mfma_f32_16x16x32_bf16 v[30:33], v[152:155], v[184:187], v[30:33]
	v_mfma_f32_16x16x32_bf16 v[26:29], v[156:159], v[180:183], v[26:29]
	v_mfma_f32_16x16x32_bf16 v[26:29], v[160:163], v[184:187], v[26:29]
	v_mfma_f32_16x16x32_bf16 v[14:17], v[148:151], v[188:191], v[14:17]
	v_mfma_f32_16x16x32_bf16 v[14:17], v[152:155], v[192:195], v[14:17]
	v_mfma_f32_16x16x32_bf16 v[10:13], v[156:159], v[188:191], v[10:13]
	v_mfma_f32_16x16x32_bf16 v[10:13], v[160:163], v[192:195], v[10:13]
	v_mfma_f32_16x16x32_bf16 v[56:59], v[132:135], v[164:167], v[56:59]
	v_mfma_f32_16x16x32_bf16 v[56:59], v[136:139], v[168:171], v[56:59]
	v_mfma_f32_16x16x32_bf16 v[52:55], v[140:143], v[164:167], v[52:55]
	v_mfma_f32_16x16x32_bf16 v[52:55], v[144:147], v[168:171], v[52:55]
	v_mfma_f32_16x16x32_bf16 v[40:43], v[132:135], v[172:175], v[40:43]
	v_mfma_f32_16x16x32_bf16 v[40:43], v[136:139], v[176:179], v[40:43]
	v_mfma_f32_16x16x32_bf16 v[36:39], v[140:143], v[172:175], v[36:39]
	v_mfma_f32_16x16x32_bf16 v[36:39], v[144:147], v[176:179], v[36:39]
	v_mfma_f32_16x16x32_bf16 v[22:25], v[132:135], v[180:183], v[22:25]
	v_mfma_f32_16x16x32_bf16 v[22:25], v[136:139], v[184:187], v[22:25]
	v_mfma_f32_16x16x32_bf16 v[18:21], v[140:143], v[180:183], v[18:21]
	v_mfma_f32_16x16x32_bf16 v[18:21], v[144:147], v[184:187], v[18:21]
	v_mfma_f32_16x16x32_bf16 v[6:9], v[132:135], v[188:191], v[6:9]
	v_mfma_f32_16x16x32_bf16 v[6:9], v[136:139], v[192:195], v[6:9]
	v_mfma_f32_16x16x32_bf16 v[2:5], v[140:143], v[188:191], v[2:5]
	v_mfma_f32_16x16x32_bf16 v[2:5], v[144:147], v[192:195], v[2:5]
	s_barrier
	s_setprio 0
	s_add_i32 s69, 0, 0x18000
	v_add_u32_e32 v34, s69, v227
	s_add_i32 s70, 0, 0x1c000
	ds_read_b128 v[132:135], v34
	ds_read_b128 v[136:139], v34 offset:1024
	ds_read_b128 v[140:143], v34 offset:2048
	ds_read_b128 v[144:147], v34 offset:3072
	v_add_u32_e32 v34, s70, v227
	ds_read_b128 v[148:151], v34
	ds_read_b128 v[152:155], v34 offset:1024
	ds_read_b128 v[156:159], v34 offset:2048
	ds_read_b128 v[160:163], v34 offset:3072
	s_add_u32 s42, s42, 0x80000
	s_addc_u32 s43, s43, 0
	s_mov_b32 m0, s61
	v_lshl_add_u64 v[246:247], s[42:43], 0, v[206:207]
	ds_read_b128 v[164:167], v240 offset:32768
	ds_read_b128 v[168:171], v240 offset:33792
	ds_read_b128 v[172:175], v240 offset:34816
	ds_read_b128 v[176:179], v240 offset:35840
	ds_read_b128 v[180:183], v240 offset:36864
	ds_read_b128 v[184:187], v240 offset:37888
	ds_read_b128 v[188:191], v240 offset:38912
	ds_read_b128 v[192:195], v240 offset:39936
	global_load_lds_dwordx4 v[246:247], off
	v_lshl_add_u64 v[246:247], s[42:43], 0, v[210:211]
	s_mov_b32 m0, s62
	s_nop 0
	global_load_lds_dwordx4 v[246:247], off
	s_waitcnt vmcnt(8)
	s_waitcnt lgkmcnt(0)
	s_setprio 1
	s_barrier
	v_mfma_f32_16x16x32_bf16 v[128:131], v[132:135], v[164:167], v[128:131]
	v_mfma_f32_16x16x32_bf16 v[128:131], v[136:139], v[168:171], v[128:131]
	v_mfma_f32_16x16x32_bf16 v[124:127], v[140:143], v[164:167], v[124:127]
	v_mfma_f32_16x16x32_bf16 v[124:127], v[144:147], v[168:171], v[124:127]
	v_mfma_f32_16x16x32_bf16 v[112:115], v[132:135], v[172:175], v[112:115]
	v_mfma_f32_16x16x32_bf16 v[112:115], v[136:139], v[176:179], v[112:115]
	v_mfma_f32_16x16x32_bf16 v[108:111], v[140:143], v[172:175], v[108:111]
	v_mfma_f32_16x16x32_bf16 v[108:111], v[144:147], v[176:179], v[108:111]
	v_mfma_f32_16x16x32_bf16 v[96:99], v[132:135], v[180:183], v[96:99]
	v_mfma_f32_16x16x32_bf16 v[96:99], v[136:139], v[184:187], v[96:99]
	v_mfma_f32_16x16x32_bf16 v[92:95], v[140:143], v[180:183], v[92:95]
	v_mfma_f32_16x16x32_bf16 v[92:95], v[144:147], v[184:187], v[92:95]
	v_mfma_f32_16x16x32_bf16 v[80:83], v[132:135], v[188:191], v[80:83]
	v_mfma_f32_16x16x32_bf16 v[80:83], v[136:139], v[192:195], v[80:83]
	v_mfma_f32_16x16x32_bf16 v[76:79], v[140:143], v[188:191], v[76:79]
	v_mfma_f32_16x16x32_bf16 v[76:79], v[144:147], v[192:195], v[76:79]
	v_mfma_f32_16x16x32_bf16 v[120:123], v[148:151], v[164:167], v[120:123]
	v_mfma_f32_16x16x32_bf16 v[120:123], v[152:155], v[168:171], v[120:123]
	v_mfma_f32_16x16x32_bf16 v[116:119], v[156:159], v[164:167], v[116:119]
	v_mfma_f32_16x16x32_bf16 v[116:119], v[160:163], v[168:171], v[116:119]
	v_mfma_f32_16x16x32_bf16 v[104:107], v[148:151], v[172:175], v[104:107]
	v_mfma_f32_16x16x32_bf16 v[104:107], v[152:155], v[176:179], v[104:107]
	v_mfma_f32_16x16x32_bf16 v[100:103], v[156:159], v[172:175], v[100:103]
	v_mfma_f32_16x16x32_bf16 v[100:103], v[160:163], v[176:179], v[100:103]
	v_mfma_f32_16x16x32_bf16 v[88:91], v[148:151], v[180:183], v[88:91]
	v_mfma_f32_16x16x32_bf16 v[88:91], v[152:155], v[184:187], v[88:91]
	v_mfma_f32_16x16x32_bf16 v[84:87], v[156:159], v[180:183], v[84:87]
	v_mfma_f32_16x16x32_bf16 v[84:87], v[160:163], v[184:187], v[84:87]
	v_mfma_f32_16x16x32_bf16 v[72:75], v[148:151], v[188:191], v[72:75]
	v_mfma_f32_16x16x32_bf16 v[72:75], v[152:155], v[192:195], v[72:75]
	v_mfma_f32_16x16x32_bf16 v[68:71], v[156:159], v[188:191], v[68:71]
	v_mfma_f32_16x16x32_bf16 v[68:71], v[160:163], v[192:195], v[68:71]
	s_barrier
	s_setprio 0
	s_add_i32 s42, s69, s46
	v_lshl_add_u64 v[198:199], v[198:199], 0, s[18:19]
	s_mov_b32 m0, s42
	ds_read_b128 v[164:167], v240 offset:49152
	ds_read_b128 v[168:171], v240 offset:50176
	ds_read_b128 v[172:175], v240 offset:51200
	ds_read_b128 v[176:179], v240 offset:52224
	ds_read_b128 v[180:183], v240 offset:53248
	ds_read_b128 v[184:187], v240 offset:54272
	ds_read_b128 v[188:191], v240 offset:55296
	ds_read_b128 v[192:195], v240 offset:56320
	global_load_lds_dwordx4 v[198:199], off
	s_add_i32 m0, s42, 0x2000
	s_add_u32 s36, s36, 0x80080
	v_lshl_add_u64 v[198:199], v[200:201], 0, s[18:19]
	s_addc_u32 s37, s37, 0
	s_add_i32 s42, s70, s46
	global_load_lds_dwordx4 v[198:199], off
	v_lshl_add_u64 v[198:199], s[36:37], 0, v[208:209]
	s_mov_b32 m0, s42
	s_nop 0
	global_load_lds_dwordx4 v[198:199], off
	v_lshl_add_u64 v[198:199], s[36:37], 0, v[212:213]
	s_add_i32 m0, s42, 0x2000
	s_nop 0
	global_load_lds_dwordx4 v[198:199], off
	v_lshl_add_u64 v[198:199], v[242:243], 0, s[18:19]
	s_mov_b32 m0, s63
	s_nop 0
	global_load_lds_dwordx4 v[198:199], off
	v_lshl_add_u64 v[198:199], v[244:245], 0, s[18:19]
	s_mov_b32 m0, s64
	s_nop 0
	global_load_lds_dwordx4 v[198:199], off
	s_waitcnt vmcnt(8)
	s_waitcnt lgkmcnt(0)
	s_setprio 1
	s_barrier
	v_mfma_f32_16x16x32_bf16 v[64:67], v[132:135], v[164:167], v[64:67]
	v_mfma_f32_16x16x32_bf16 v[64:67], v[136:139], v[168:171], v[64:67]
	v_mfma_f32_16x16x32_bf16 v[60:63], v[140:143], v[164:167], v[60:63]
	v_mfma_f32_16x16x32_bf16 v[60:63], v[144:147], v[168:171], v[60:63]
	v_mfma_f32_16x16x32_bf16 v[48:51], v[132:135], v[172:175], v[48:51]
	v_mfma_f32_16x16x32_bf16 v[48:51], v[136:139], v[176:179], v[48:51]
	v_mfma_f32_16x16x32_bf16 v[44:47], v[140:143], v[172:175], v[44:47]
	v_mfma_f32_16x16x32_bf16 v[44:47], v[144:147], v[176:179], v[44:47]
	v_mfma_f32_16x16x32_bf16 v[30:33], v[132:135], v[180:183], v[30:33]
	v_mfma_f32_16x16x32_bf16 v[30:33], v[136:139], v[184:187], v[30:33]
	v_mfma_f32_16x16x32_bf16 v[26:29], v[140:143], v[180:183], v[26:29]
	v_mfma_f32_16x16x32_bf16 v[26:29], v[144:147], v[184:187], v[26:29]
	v_mfma_f32_16x16x32_bf16 v[14:17], v[132:135], v[188:191], v[14:17]
	v_mfma_f32_16x16x32_bf16 v[14:17], v[136:139], v[192:195], v[14:17]
	v_mfma_f32_16x16x32_bf16 v[10:13], v[140:143], v[188:191], v[10:13]
	v_mfma_f32_16x16x32_bf16 v[10:13], v[144:147], v[192:195], v[10:13]
	v_mfma_f32_16x16x32_bf16 v[56:59], v[148:151], v[164:167], v[56:59]
	v_mfma_f32_16x16x32_bf16 v[56:59], v[152:155], v[168:171], v[56:59]
	v_mfma_f32_16x16x32_bf16 v[52:55], v[156:159], v[164:167], v[52:55]
	v_mfma_f32_16x16x32_bf16 v[52:55], v[160:163], v[168:171], v[52:55]
	v_mfma_f32_16x16x32_bf16 v[40:43], v[148:151], v[172:175], v[40:43]
	v_mfma_f32_16x16x32_bf16 v[40:43], v[152:155], v[176:179], v[40:43]
	v_mfma_f32_16x16x32_bf16 v[36:39], v[156:159], v[172:175], v[36:39]
	v_mfma_f32_16x16x32_bf16 v[36:39], v[160:163], v[176:179], v[36:39]
	v_mfma_f32_16x16x32_bf16 v[22:25], v[148:151], v[180:183], v[22:25]
	v_mfma_f32_16x16x32_bf16 v[22:25], v[152:155], v[184:187], v[22:25]
	v_mfma_f32_16x16x32_bf16 v[18:21], v[156:159], v[180:183], v[18:21]
	v_mfma_f32_16x16x32_bf16 v[18:21], v[160:163], v[184:187], v[18:21]
	v_mfma_f32_16x16x32_bf16 v[6:9], v[148:151], v[188:191], v[6:9]
	v_mfma_f32_16x16x32_bf16 v[6:9], v[152:155], v[192:195], v[6:9]
	v_mfma_f32_16x16x32_bf16 v[2:5], v[156:159], v[188:191], v[2:5]
	v_mfma_f32_16x16x32_bf16 v[2:5], v[160:163], v[192:195], v[2:5]
	s_barrier
	s_setprio 0
	s_add_i32 s68, s68, 2
	s_add_u32 s34, s34, 0x100
	s_addc_u32 s35, s35, 0
	s_cmp_gt_u32 s68, 29
	s_cbranch_scc0 .LBB0_808
	s_branch .LBB0_810
.Lrss_win:
	s_add_i32 m0, s47, 0x21200
	s_nop 0
	global_load_lds_dwordx4 v[220:221], off
	s_branch .LBB0_807

.LBB0_1642:
	s_ashr_i32 s23, s22, 31
	s_lshl_b64 s[24:25], s[22:23], 20
	s_add_u32 s24, s44, s24
	s_addc_u32 s25, s45, s25
	s_and_b64 s[26:27], s[38:39], exec
	s_cselect_b32 s13, s25, s35
	s_cselect_b32 s23, s24, s34
	s_ashr_i32 s21, s20, 31
	s_lshl_b64 s[26:27], s[20:21], 20
	s_add_u32 s26, s46, s26
	s_addc_u32 s27, s47, s27
	s_and_b64 s[28:29], s[38:39], exec
	s_cselect_b32 s21, s27, s37
	s_cselect_b32 s76, s26, s36
	s_ashr_i32 s31, s30, 31
	s_lshl_b64 s[28:29], s[30:31], 13
	s_add_u32 s40, s34, 0x80080
	s_addc_u32 s41, s35, 0
	v_mov_b32_e32 v34, v35
	v_mov_b32_e32 v36, v35
	v_mov_b32_e32 v37, v35
	s_add_u32 s31, s36, 0x100
	v_mov_b64_e32 v[2:3], v[34:35]
	v_mov_b64_e32 v[6:7], v[34:35]
	v_mov_b64_e32 v[18:19], v[34:35]
	v_mov_b64_e32 v[22:23], v[34:35]
	v_mov_b64_e32 v[40:41], v[36:37]
	v_mov_b64_e32 v[44:45], v[36:37]
	v_mov_b64_e32 v[56:57], v[36:37]
	v_mov_b64_e32 v[60:61], v[36:37]
	v_mov_b64_e32 v[10:11], v[34:35]
	v_mov_b64_e32 v[14:15], v[34:35]
	v_mov_b64_e32 v[26:27], v[34:35]
	v_mov_b64_e32 v[30:31], v[34:35]
	v_mov_b64_e32 v[48:49], v[36:37]
	v_mov_b64_e32 v[52:53], v[36:37]
	v_mov_b64_e32 v[64:65], v[36:37]
	v_mov_b64_e32 v[68:69], v[36:37]
	v_mov_b64_e32 v[72:73], v[36:37]
	v_mov_b64_e32 v[76:77], v[36:37]
	v_mov_b64_e32 v[88:89], v[36:37]
	v_mov_b64_e32 v[92:93], v[36:37]
	v_mov_b64_e32 v[104:105], v[36:37]
	v_mov_b64_e32 v[108:109], v[36:37]
	v_mov_b64_e32 v[120:121], v[36:37]
	v_mov_b64_e32 v[124:125], v[36:37]
	v_mov_b64_e32 v[80:81], v[36:37]
	v_mov_b64_e32 v[84:85], v[36:37]
	v_mov_b64_e32 v[96:97], v[36:37]
	v_mov_b64_e32 v[100:101], v[36:37]
	v_mov_b64_e32 v[112:113], v[36:37]
	v_mov_b64_e32 v[116:117], v[36:37]
	v_mov_b64_e32 v[128:129], v[36:37]
	v_mov_b64_e32 v[132:133], v[36:37]
	v_lshl_add_u64 v[222:223], v[216:217], 0, s[28:29]
	v_lshl_add_u64 v[224:225], s[40:41], 0, v[218:219]
	v_lshl_add_u64 v[226:227], s[40:41], 0, v[220:221]
	s_addc_u32 s77, s37, 0
	s_mov_b32 vcc_lo, -2
	s_mov_b64 s[36:37], 0
	v_mov_b64_e32 v[4:5], v[36:37]
	v_mov_b64_e32 v[8:9], v[36:37]
	v_mov_b64_e32 v[20:21], v[36:37]
	v_mov_b64_e32 v[24:25], v[36:37]
	v_mov_b64_e32 v[38:39], v[34:35]
	v_mov_b64_e32 v[42:43], v[34:35]
	v_mov_b64_e32 v[54:55], v[34:35]
	v_mov_b64_e32 v[58:59], v[34:35]
	v_mov_b64_e32 v[12:13], v[36:37]
	v_mov_b64_e32 v[16:17], v[36:37]
	v_mov_b64_e32 v[28:29], v[36:37]
	v_mov_b64_e32 v[32:33], v[36:37]
	v_mov_b64_e32 v[46:47], v[34:35]
	v_mov_b64_e32 v[50:51], v[34:35]
	v_mov_b64_e32 v[62:63], v[34:35]
	v_mov_b64_e32 v[66:67], v[34:35]
	v_mov_b64_e32 v[70:71], v[34:35]
	v_mov_b64_e32 v[74:75], v[34:35]
	v_mov_b64_e32 v[86:87], v[34:35]
	v_mov_b64_e32 v[90:91], v[34:35]
	v_mov_b64_e32 v[102:103], v[34:35]
	v_mov_b64_e32 v[106:107], v[34:35]
	v_mov_b64_e32 v[118:119], v[34:35]
	v_mov_b64_e32 v[122:123], v[34:35]
	v_mov_b64_e32 v[78:79], v[34:35]
	v_mov_b64_e32 v[82:83], v[34:35]
	v_mov_b64_e32 v[94:95], v[34:35]
	v_mov_b64_e32 v[98:99], v[34:35]
	v_mov_b64_e32 v[110:111], v[34:35]
	v_mov_b64_e32 v[114:115], v[34:35]
	v_mov_b64_e32 v[126:127], v[34:35]
	v_mov_b64_e32 v[130:131], v[34:35]
	s_branch .LBB0_1644
.LBB0_1644:
	s_cmpk_lg_i32 s36, 0x800
	s_cbranch_scc1 .LBB0_1646
	v_add_u32_e32 v34, s67, v243
	ds_read_b128 v[134:137], v34
	ds_read_b128 v[138:141], v34 offset:16
	s_waitcnt lgkmcnt(0)
	v_mov_b32_e32 v36, v134
	v_mov_b32_e32 v37, v138
	v_mov_b32_e32 v138, v135
	v_mov_b32_e32 v134, v136
	v_mov_b32_e32 v135, v140
	v_mov_b32_e32 v140, v137
	v_pk_add_f32 v[36:37], v[36:37], v[138:139]
	v_pk_add_f32 v[134:135], v[134:135], v[140:141]
	s_nop 0
	v_pk_add_f32 v[36:37], v[36:37], v[134:135]
	s_nop 0
	v_add_f32_e32 v34, v36, v37
	v_add_u32_e32 v36, s68, v243
	ds_read_b128 v[134:137], v36
	ds_read_b128 v[138:141], v36 offset:16
	v_fmamk_f32 v34, v34, 0x3a800000, v1
	v_sqrt_f32_e32 v34, v34
	s_waitcnt lgkmcnt(0)
	v_mov_b32_e32 v36, v134
	v_mov_b32_e32 v37, v138
	v_mov_b32_e32 v138, v135
	v_mov_b32_e32 v134, v136
	v_mov_b32_e32 v135, v140
	v_mov_b32_e32 v140, v137
	v_pk_add_f32 v[36:37], v[36:37], v[138:139]
	v_pk_add_f32 v[134:135], v[134:135], v[140:141]
	v_pk_mul_f32 v[132:133], v[132:133], v[34:35] op_sel_hi:[1,0]
	v_pk_add_f32 v[36:37], v[36:37], v[134:135]
	v_pk_mul_f32 v[130:131], v[130:131], v[34:35] op_sel_hi:[1,0]
	v_add_f32_e32 v36, v36, v37
	v_add_u32_e32 v37, s69, v243
	ds_read_b128 v[134:137], v37
	ds_read_b128 v[138:141], v37 offset:16
	v_fmamk_f32 v36, v36, 0x3a800000, v1
	v_sqrt_f32_e32 v36, v36
	v_pk_mul_f32 v[128:129], v[128:129], v[34:35] op_sel_hi:[1,0]
	s_waitcnt lgkmcnt(0)
	v_mov_b32_e32 v142, v134
	v_mov_b32_e32 v143, v138
	v_mov_b32_e32 v138, v135
	v_pk_add_f32 v[134:135], v[142:143], v[138:139]
	v_mov_b32_e32 v138, v136
	v_mov_b32_e32 v139, v140
	v_mov_b32_e32 v140, v137
	v_pk_add_f32 v[136:137], v[138:139], v[140:141]
	v_pk_mul_f32 v[116:117], v[116:117], v[36:37] op_sel_hi:[1,0]
	v_pk_add_f32 v[134:135], v[134:135], v[136:137]
	v_pk_mul_f32 v[114:115], v[114:115], v[36:37] op_sel_hi:[1,0]
	v_add_f32_e32 v37, v134, v135
	v_fmamk_f32 v37, v37, 0x3a800000, v1
	v_sqrt_f32_e32 v142, v37
	v_add_u32_e32 v37, s70, v243
	ds_read_b128 v[134:137], v37
	ds_read_b128 v[138:141], v37 offset:16
	v_pk_mul_f32 v[126:127], v[126:127], v[34:35] op_sel_hi:[1,0]
	v_pk_mul_f32 v[124:125], v[124:125], v[34:35] op_sel_hi:[1,0]
	v_pk_mul_f32 v[122:123], v[122:123], v[34:35] op_sel_hi:[1,0]
	s_waitcnt lgkmcnt(0)
	v_mov_b32_e32 v144, v134
	v_mov_b32_e32 v145, v138
	v_mov_b32_e32 v138, v135
	v_pk_add_f32 v[134:135], v[144:145], v[138:139]
	v_mov_b32_e32 v138, v136
	v_mov_b32_e32 v139, v140
	v_mov_b32_e32 v140, v137
	v_pk_add_f32 v[136:137], v[138:139], v[140:141]
	v_pk_mul_f32 v[120:121], v[120:121], v[34:35] op_sel_hi:[1,0]
	v_pk_add_f32 v[134:135], v[134:135], v[136:137]
	v_pk_mul_f32 v[118:119], v[118:119], v[34:35] op_sel_hi:[1,0]
	v_add_u32_e32 v34, s71, v243
	v_pk_mul_f32 v[112:113], v[112:113], v[36:37] op_sel_hi:[1,0]
	v_pk_mul_f32 v[110:111], v[110:111], v[36:37] op_sel_hi:[1,0]
	v_add_f32_e32 v37, v134, v135
	ds_read_b128 v[134:137], v34
	ds_read_b128 v[138:141], v34 offset:16
	v_fmamk_f32 v37, v37, 0x3a800000, v1
	v_sqrt_f32_e32 v144, v37
	v_pk_mul_f32 v[108:109], v[108:109], v[36:37] op_sel_hi:[1,0]
	v_pk_mul_f32 v[106:107], v[106:107], v[36:37] op_sel_hi:[1,0]
	v_pk_mul_f32 v[104:105], v[104:105], v[36:37] op_sel_hi:[1,0]
	v_pk_mul_f32 v[102:103], v[102:103], v[36:37] op_sel_hi:[1,0]
	s_waitcnt lgkmcnt(0)
	v_mov_b32_e32 v36, v134
	v_mov_b32_e32 v37, v138
	v_mov_b32_e32 v138, v135
	v_mov_b32_e32 v134, v136
	v_mov_b32_e32 v135, v140
	v_mov_b32_e32 v140, v137
	v_pk_add_f32 v[36:37], v[36:37], v[138:139]
	v_pk_add_f32 v[134:135], v[134:135], v[140:141]
	v_pk_mul_f32 v[100:101], v[100:101], v[142:143] op_sel_hi:[1,0]
	v_pk_add_f32 v[36:37], v[36:37], v[134:135]
	v_pk_mul_f32 v[98:99], v[98:99], v[142:143] op_sel_hi:[1,0]
	v_add_f32_e32 v34, v36, v37
	v_add_u32_e32 v36, s72, v243
	ds_read_b128 v[134:137], v36
	ds_read_b128 v[138:141], v36 offset:16
	v_fmamk_f32 v34, v34, 0x3a800000, v1
	v_sqrt_f32_e32 v34, v34
	v_pk_mul_f32 v[96:97], v[96:97], v[142:143] op_sel_hi:[1,0]
	s_waitcnt lgkmcnt(0)
	v_mov_b32_e32 v36, v134
	v_mov_b32_e32 v37, v138
	v_mov_b32_e32 v138, v135
	v_mov_b32_e32 v134, v136
	v_mov_b32_e32 v135, v140
	v_mov_b32_e32 v140, v137
	v_pk_mul_f32 v[68:69], v[68:69], v[34:35] op_sel_hi:[1,0]
	v_pk_mul_f32 v[66:67], v[66:67], v[34:35] op_sel_hi:[1,0]
	v_pk_mul_f32 v[64:65], v[64:65], v[34:35] op_sel_hi:[1,0]
	v_pk_mul_f32 v[62:63], v[62:63], v[34:35] op_sel_hi:[1,0]
	v_pk_mul_f32 v[60:61], v[60:61], v[34:35] op_sel_hi:[1,0]
	v_pk_add_f32 v[36:37], v[36:37], v[138:139]
	v_pk_add_f32 v[134:135], v[134:135], v[140:141]
	v_pk_mul_f32 v[58:59], v[58:59], v[34:35] op_sel_hi:[1,0]
	v_pk_mul_f32 v[56:57], v[56:57], v[34:35] op_sel_hi:[1,0]
	v_pk_mul_f32 v[54:55], v[54:55], v[34:35] op_sel_hi:[1,0]
	v_add_u32_e32 v34, s73, v243
	v_pk_add_f32 v[36:37], v[36:37], v[134:135]
	ds_read_b128 v[134:137], v34
	ds_read_b128 v[138:141], v34 offset:16
	v_add_f32_e32 v36, v36, v37
	v_fmamk_f32 v36, v36, 0x3a800000, v1
	v_sqrt_f32_e32 v36, v36
	v_pk_mul_f32 v[94:95], v[94:95], v[142:143] op_sel_hi:[1,0]
	v_pk_mul_f32 v[92:93], v[92:93], v[142:143] op_sel_hi:[1,0]
	v_pk_mul_f32 v[90:91], v[90:91], v[142:143] op_sel_hi:[1,0]
	v_pk_mul_f32 v[88:89], v[88:89], v[142:143] op_sel_hi:[1,0]
	v_pk_mul_f32 v[86:87], v[86:87], v[142:143] op_sel_hi:[1,0]
	s_waitcnt lgkmcnt(0)
	v_mov_b32_e32 v142, v134
	v_mov_b32_e32 v143, v138
	v_mov_b32_e32 v138, v135
	v_pk_add_f32 v[134:135], v[142:143], v[138:139]
	v_mov_b32_e32 v138, v136
	v_mov_b32_e32 v139, v140
	v_mov_b32_e32 v140, v137
	v_pk_add_f32 v[136:137], v[138:139], v[140:141]
	v_pk_mul_f32 v[52:53], v[52:53], v[36:37] op_sel_hi:[1,0]
	v_pk_mul_f32 v[50:51], v[50:51], v[36:37] op_sel_hi:[1,0]
	v_pk_mul_f32 v[48:49], v[48:49], v[36:37] op_sel_hi:[1,0]
	v_pk_mul_f32 v[46:47], v[46:47], v[36:37] op_sel_hi:[1,0]
	v_pk_mul_f32 v[44:45], v[44:45], v[36:37] op_sel_hi:[1,0]
	v_pk_add_f32 v[134:135], v[134:135], v[136:137]
	v_pk_mul_f32 v[42:43], v[42:43], v[36:37] op_sel_hi:[1,0]
	v_pk_mul_f32 v[40:41], v[40:41], v[36:37] op_sel_hi:[1,0]
	v_pk_mul_f32 v[38:39], v[38:39], v[36:37] op_sel_hi:[1,0]
	v_add_u32_e32 v36, s74, v243
	v_add_f32_e32 v34, v134, v135
	ds_read_b128 v[134:137], v36
	ds_read_b128 v[138:141], v36 offset:16
	v_fmamk_f32 v34, v34, 0x3a800000, v1
	v_sqrt_f32_e32 v34, v34
	v_pk_mul_f32 v[84:85], v[84:85], v[144:145] op_sel_hi:[1,0]
	s_waitcnt lgkmcnt(0)
	v_mov_b32_e32 v36, v134
	v_mov_b32_e32 v37, v138
	v_mov_b32_e32 v138, v135
	v_mov_b32_e32 v134, v136
	v_mov_b32_e32 v135, v140
	v_mov_b32_e32 v140, v137
	v_pk_add_f32 v[36:37], v[36:37], v[138:139]
	v_pk_add_f32 v[134:135], v[134:135], v[140:141]
	v_pk_mul_f32 v[82:83], v[82:83], v[144:145] op_sel_hi:[1,0]
	v_pk_add_f32 v[36:37], v[36:37], v[134:135]
	v_pk_mul_f32 v[80:81], v[80:81], v[144:145] op_sel_hi:[1,0]
	v_add_f32_e32 v36, v36, v37
	v_fmamk_f32 v36, v36, 0x3a800000, v1
	v_sqrt_f32_e32 v36, v36
	v_pk_mul_f32 v[78:79], v[78:79], v[144:145] op_sel_hi:[1,0]
	v_pk_mul_f32 v[76:77], v[76:77], v[144:145] op_sel_hi:[1,0]
	v_pk_mul_f32 v[74:75], v[74:75], v[144:145] op_sel_hi:[1,0]
	v_pk_mul_f32 v[72:73], v[72:73], v[144:145] op_sel_hi:[1,0]
	v_pk_mul_f32 v[70:71], v[70:71], v[144:145] op_sel_hi:[1,0]
	v_pk_mul_f32 v[32:33], v[32:33], v[34:35] op_sel_hi:[1,0]
	v_pk_mul_f32 v[30:31], v[30:31], v[34:35] op_sel_hi:[1,0]
	v_pk_mul_f32 v[28:29], v[28:29], v[34:35] op_sel_hi:[1,0]
	v_pk_mul_f32 v[26:27], v[26:27], v[34:35] op_sel_hi:[1,0]
	v_pk_mul_f32 v[24:25], v[24:25], v[34:35] op_sel_hi:[1,0]
	v_pk_mul_f32 v[22:23], v[22:23], v[34:35] op_sel_hi:[1,0]
	v_pk_mul_f32 v[20:21], v[20:21], v[34:35] op_sel_hi:[1,0]
	v_pk_mul_f32 v[18:19], v[18:19], v[34:35] op_sel_hi:[1,0]
	v_pk_mul_f32 v[16:17], v[16:17], v[36:37] op_sel_hi:[1,0]
	v_pk_mul_f32 v[14:15], v[14:15], v[36:37] op_sel_hi:[1,0]
	v_pk_mul_f32 v[12:13], v[12:13], v[36:37] op_sel_hi:[1,0]
	v_pk_mul_f32 v[10:11], v[10:11], v[36:37] op_sel_hi:[1,0]
	v_pk_mul_f32 v[8:9], v[8:9], v[36:37] op_sel_hi:[1,0]
	v_pk_mul_f32 v[6:7], v[6:7], v[36:37] op_sel_hi:[1,0]
	v_pk_mul_f32 v[4:5], v[4:5], v[36:37] op_sel_hi:[1,0]
	v_pk_mul_f32 v[2:3], v[2:3], v[36:37] op_sel_hi:[1,0]
.LBB0_1646:
	v_add_u32_e32 v34, 0, v242
	v_add_u32_e32 v36, 0x10000, v34
	v_add_u32_e32 v34, 0x14000, v34
	ds_read_b128 v[150:153], v36
	ds_read_b128 v[154:157], v36 offset:1024
	ds_read_b128 v[158:161], v36 offset:2048
	ds_read_b128 v[162:165], v36 offset:3072
	ds_read_b128 v[134:137], v34
	ds_read_b128 v[138:141], v34 offset:1024
	ds_read_b128 v[142:145], v34 offset:2048
	ds_read_b128 v[146:149], v34 offset:3072
	v_lshl_add_u64 v[36:37], v[224:225], 0, s[36:37]
	s_add_i32 m0, s54, 0xc000
	ds_read_b128 v[190:193], v244
	ds_read_b128 v[194:197], v244 offset:1024
	ds_read_b128 v[182:185], v244 offset:2048
	ds_read_b128 v[186:189], v244 offset:3072
	ds_read_b128 v[174:177], v244 offset:4096
	ds_read_b128 v[178:181], v244 offset:5120
	ds_read_b128 v[166:169], v244 offset:6144
	ds_read_b128 v[170:173], v244 offset:7168
	global_load_lds_dwordx4 v[36:37], off
	v_lshl_add_u64 v[36:37], v[226:227], 0, s[36:37]
	s_add_i32 m0, s54, 0xe000
	s_cmp_lg_u32 s36, 0
	global_load_lds_dwordx4 v[36:37], off
	s_waitcnt vmcnt(8)
	s_waitcnt lgkmcnt(0)
	s_add_u32 s40, s34, s36
	s_addc_u32 s41, s35, s37
	s_add_u32 s40, s40, 0x100
	s_addc_u32 s41, s41, 0
	s_add_u32 s78, s31, s36
	s_addc_u32 s79, s77, s37
	s_cmpk_eq_i32 s36, 0xf00
	s_cselect_b32 s43, s13, s41
	s_cselect_b32 s42, s23, s40
	s_cselect_b32 s41, s21, s79
	s_cselect_b32 s40, s76, s78
	s_cmp_lg_u32 s36, 0
	s_setprio 1
	s_barrier
	s_cbranch_scc0 .Lrss_wout
.LBB0_1643:
	v_mfma_f32_16x16x32_bf16 v[130:133], v[150:153], v[190:193], v[130:133]
	v_mfma_f32_16x16x32_bf16 v[130:133], v[154:157], v[194:197], v[130:133]
	v_mfma_f32_16x16x32_bf16 v[126:129], v[158:161], v[190:193], v[126:129]
	v_mfma_f32_16x16x32_bf16 v[126:129], v[162:165], v[194:197], v[126:129]
	v_mfma_f32_16x16x32_bf16 v[114:117], v[150:153], v[182:185], v[114:117]
	v_mfma_f32_16x16x32_bf16 v[114:117], v[154:157], v[186:189], v[114:117]
	v_mfma_f32_16x16x32_bf16 v[110:113], v[158:161], v[182:185], v[110:113]
	v_mfma_f32_16x16x32_bf16 v[110:113], v[162:165], v[186:189], v[110:113]
	v_mfma_f32_16x16x32_bf16 v[98:101], v[150:153], v[174:177], v[98:101]
	v_mfma_f32_16x16x32_bf16 v[98:101], v[154:157], v[178:181], v[98:101]
	v_mfma_f32_16x16x32_bf16 v[94:97], v[158:161], v[174:177], v[94:97]
	v_mfma_f32_16x16x32_bf16 v[94:97], v[162:165], v[178:181], v[94:97]
	v_mfma_f32_16x16x32_bf16 v[82:85], v[150:153], v[166:169], v[82:85]
	v_mfma_f32_16x16x32_bf16 v[82:85], v[154:157], v[170:173], v[82:85]
	v_mfma_f32_16x16x32_bf16 v[78:81], v[158:161], v[166:169], v[78:81]
	v_mfma_f32_16x16x32_bf16 v[78:81], v[162:165], v[170:173], v[78:81]
	v_mfma_f32_16x16x32_bf16 v[122:125], v[134:137], v[190:193], v[122:125]
	v_mfma_f32_16x16x32_bf16 v[122:125], v[138:141], v[194:197], v[122:125]
	v_mfma_f32_16x16x32_bf16 v[118:121], v[142:145], v[190:193], v[118:121]
	v_mfma_f32_16x16x32_bf16 v[118:121], v[146:149], v[194:197], v[118:121]
	v_mfma_f32_16x16x32_bf16 v[106:109], v[134:137], v[182:185], v[106:109]
	v_mfma_f32_16x16x32_bf16 v[106:109], v[138:141], v[186:189], v[106:109]
	v_mfma_f32_16x16x32_bf16 v[102:105], v[142:145], v[182:185], v[102:105]
	v_mfma_f32_16x16x32_bf16 v[102:105], v[146:149], v[186:189], v[102:105]
	v_mfma_f32_16x16x32_bf16 v[90:93], v[134:137], v[174:177], v[90:93]
	v_mfma_f32_16x16x32_bf16 v[90:93], v[138:141], v[178:181], v[90:93]
	v_mfma_f32_16x16x32_bf16 v[86:89], v[142:145], v[174:177], v[86:89]
	v_mfma_f32_16x16x32_bf16 v[86:89], v[146:149], v[178:181], v[86:89]
	v_mfma_f32_16x16x32_bf16 v[74:77], v[134:137], v[166:169], v[74:77]
	v_mfma_f32_16x16x32_bf16 v[74:77], v[138:141], v[170:173], v[74:77]
	v_mfma_f32_16x16x32_bf16 v[70:73], v[142:145], v[166:169], v[70:73]
	v_mfma_f32_16x16x32_bf16 v[70:73], v[146:149], v[170:173], v[70:73]
	s_barrier
	s_setprio 0
	s_mov_b32 m0, s55
	v_lshl_add_u64 v[198:199], s[40:41], 0, v[210:211]
	s_add_u32 s78, s40, 0x80000
	ds_read_b128 v[166:169], v244 offset:16384
	ds_read_b128 v[170:173], v244 offset:17408
	ds_read_b128 v[174:177], v244 offset:18432
	ds_read_b128 v[178:181], v244 offset:19456
	ds_read_b128 v[182:185], v244 offset:20480
	ds_read_b128 v[186:189], v244 offset:21504
	ds_read_b128 v[190:193], v244 offset:22528
	ds_read_b128 v[194:197], v244 offset:23552
	global_load_lds_dwordx4 v[198:199], off
	v_lshl_add_u64 v[200:201], s[40:41], 0, v[214:215]
	s_mov_b32 m0, s59
	s_addc_u32 s79, s41, 0
	global_load_lds_dwordx4 v[200:201], off
	v_lshl_add_u64 v[36:37], s[78:79], 0, v[210:211]
	s_mov_b32 m0, s60
	v_lshl_add_u64 v[246:247], s[42:43], 0, v[208:209]
	global_load_lds_dwordx4 v[36:37], off
	v_lshl_add_u64 v[36:37], s[78:79], 0, v[214:215]
	s_mov_b32 m0, s61
	v_lshl_add_u64 v[248:249], s[42:43], 0, v[212:213]
	global_load_lds_dwordx4 v[36:37], off
	s_mov_b32 m0, s54
	s_nop 0
	global_load_lds_dwordx4 v[246:247], off
	s_mov_b32 m0, s62
	s_nop 0
	global_load_lds_dwordx4 v[248:249], off
	s_waitcnt vmcnt(8)
	s_waitcnt lgkmcnt(0)
	s_setprio 1
	s_barrier
	v_mfma_f32_16x16x32_bf16 v[66:69], v[150:153], v[166:169], v[66:69]
	v_mfma_f32_16x16x32_bf16 v[66:69], v[154:157], v[170:173], v[66:69]
	v_mfma_f32_16x16x32_bf16 v[62:65], v[158:161], v[166:169], v[62:65]
	v_mfma_f32_16x16x32_bf16 v[62:65], v[162:165], v[170:173], v[62:65]
	v_mfma_f32_16x16x32_bf16 v[50:53], v[150:153], v[174:177], v[50:53]
	v_mfma_f32_16x16x32_bf16 v[50:53], v[154:157], v[178:181], v[50:53]
	v_mfma_f32_16x16x32_bf16 v[46:49], v[158:161], v[174:177], v[46:49]
	v_mfma_f32_16x16x32_bf16 v[46:49], v[162:165], v[178:181], v[46:49]
	v_mfma_f32_16x16x32_bf16 v[30:33], v[150:153], v[182:185], v[30:33]
	v_mfma_f32_16x16x32_bf16 v[30:33], v[154:157], v[186:189], v[30:33]
	v_mfma_f32_16x16x32_bf16 v[26:29], v[158:161], v[182:185], v[26:29]
	v_mfma_f32_16x16x32_bf16 v[26:29], v[162:165], v[186:189], v[26:29]
	v_mfma_f32_16x16x32_bf16 v[14:17], v[150:153], v[190:193], v[14:17]
	v_mfma_f32_16x16x32_bf16 v[14:17], v[154:157], v[194:197], v[14:17]
	v_mfma_f32_16x16x32_bf16 v[10:13], v[158:161], v[190:193], v[10:13]
	v_mfma_f32_16x16x32_bf16 v[10:13], v[162:165], v[194:197], v[10:13]
	v_mfma_f32_16x16x32_bf16 v[58:61], v[134:137], v[166:169], v[58:61]
	v_mfma_f32_16x16x32_bf16 v[58:61], v[138:141], v[170:173], v[58:61]
	v_mfma_f32_16x16x32_bf16 v[54:57], v[142:145], v[166:169], v[54:57]
	v_mfma_f32_16x16x32_bf16 v[54:57], v[146:149], v[170:173], v[54:57]
	v_mfma_f32_16x16x32_bf16 v[42:45], v[134:137], v[174:177], v[42:45]
	v_mfma_f32_16x16x32_bf16 v[42:45], v[138:141], v[178:181], v[42:45]
	v_mfma_f32_16x16x32_bf16 v[36:39], v[142:145], v[174:177], v[38:41]
	v_mfma_f32_16x16x32_bf16 v[36:39], v[146:149], v[178:181], v[36:39]
	v_mfma_f32_16x16x32_bf16 v[22:25], v[134:137], v[182:185], v[22:25]
	v_mfma_f32_16x16x32_bf16 v[22:25], v[138:141], v[186:189], v[22:25]
	v_mfma_f32_16x16x32_bf16 v[18:21], v[142:145], v[182:185], v[18:21]
	v_mfma_f32_16x16x32_bf16 v[18:21], v[146:149], v[186:189], v[18:21]
	v_mfma_f32_16x16x32_bf16 v[6:9], v[134:137], v[190:193], v[6:9]
	v_mfma_f32_16x16x32_bf16 v[6:9], v[138:141], v[194:197], v[6:9]
	v_mfma_f32_16x16x32_bf16 v[2:5], v[142:145], v[190:193], v[2:5]
	v_mfma_f32_16x16x32_bf16 v[2:5], v[146:149], v[194:197], v[2:5]
	s_barrier
	s_setprio 0
	s_add_i32 s78, 0, 0x18000
	v_add_u32_e32 v34, s78, v242
	s_add_i32 s79, 0, 0x1c000
	ds_read_b128 v[134:137], v34
	ds_read_b128 v[138:141], v34 offset:1024
	ds_read_b128 v[142:145], v34 offset:2048
	ds_read_b128 v[146:149], v34 offset:3072
	v_add_u32_e32 v34, s79, v242
	ds_read_b128 v[150:153], v34
	ds_read_b128 v[154:157], v34 offset:1024
	ds_read_b128 v[158:161], v34 offset:2048
	ds_read_b128 v[162:165], v34 offset:3072
	s_add_u32 s42, s42, 0x80000
	s_addc_u32 s43, s43, 0
	s_mov_b32 m0, s63
	v_lshl_add_u64 v[40:41], s[42:43], 0, v[208:209]
	ds_read_b128 v[166:169], v244 offset:32768
	ds_read_b128 v[170:173], v244 offset:33792
	ds_read_b128 v[174:177], v244 offset:34816
	ds_read_b128 v[178:181], v244 offset:35840
	ds_read_b128 v[182:185], v244 offset:36864
	ds_read_b128 v[186:189], v244 offset:37888
	ds_read_b128 v[190:193], v244 offset:38912
	ds_read_b128 v[194:197], v244 offset:39936
	global_load_lds_dwordx4 v[40:41], off
	v_lshl_add_u64 v[40:41], s[42:43], 0, v[212:213]
	s_mov_b32 m0, s64
	s_nop 0
	global_load_lds_dwordx4 v[40:41], off
	s_waitcnt vmcnt(8)
	s_waitcnt lgkmcnt(0)
	s_setprio 1
	s_barrier
	v_mfma_f32_16x16x32_bf16 v[130:133], v[134:137], v[166:169], v[130:133]
	v_mfma_f32_16x16x32_bf16 v[130:133], v[138:141], v[170:173], v[130:133]
	v_mfma_f32_16x16x32_bf16 v[126:129], v[142:145], v[166:169], v[126:129]
	v_mfma_f32_16x16x32_bf16 v[126:129], v[146:149], v[170:173], v[126:129]
	v_mfma_f32_16x16x32_bf16 v[114:117], v[134:137], v[174:177], v[114:117]
	v_mfma_f32_16x16x32_bf16 v[114:117], v[138:141], v[178:181], v[114:117]
	v_mfma_f32_16x16x32_bf16 v[110:113], v[142:145], v[174:177], v[110:113]
	v_mfma_f32_16x16x32_bf16 v[110:113], v[146:149], v[178:181], v[110:113]
	v_mfma_f32_16x16x32_bf16 v[98:101], v[134:137], v[182:185], v[98:101]
	v_mfma_f32_16x16x32_bf16 v[98:101], v[138:141], v[186:189], v[98:101]
	v_mfma_f32_16x16x32_bf16 v[94:97], v[142:145], v[182:185], v[94:97]
	v_mfma_f32_16x16x32_bf16 v[94:97], v[146:149], v[186:189], v[94:97]
	v_mfma_f32_16x16x32_bf16 v[82:85], v[134:137], v[190:193], v[82:85]
	v_mfma_f32_16x16x32_bf16 v[82:85], v[138:141], v[194:197], v[82:85]
	v_mfma_f32_16x16x32_bf16 v[78:81], v[142:145], v[190:193], v[78:81]
	v_mfma_f32_16x16x32_bf16 v[78:81], v[146:149], v[194:197], v[78:81]
	v_mfma_f32_16x16x32_bf16 v[122:125], v[150:153], v[166:169], v[122:125]
	v_mfma_f32_16x16x32_bf16 v[122:125], v[154:157], v[170:173], v[122:125]
	v_mfma_f32_16x16x32_bf16 v[118:121], v[158:161], v[166:169], v[118:121]
	v_mfma_f32_16x16x32_bf16 v[118:121], v[162:165], v[170:173], v[118:121]
	v_mfma_f32_16x16x32_bf16 v[106:109], v[150:153], v[174:177], v[106:109]
	v_mfma_f32_16x16x32_bf16 v[106:109], v[154:157], v[178:181], v[106:109]
	v_mfma_f32_16x16x32_bf16 v[102:105], v[158:161], v[174:177], v[102:105]
	v_mfma_f32_16x16x32_bf16 v[102:105], v[162:165], v[178:181], v[102:105]
	v_mfma_f32_16x16x32_bf16 v[90:93], v[150:153], v[182:185], v[90:93]
	v_mfma_f32_16x16x32_bf16 v[90:93], v[154:157], v[186:189], v[90:93]
	v_mfma_f32_16x16x32_bf16 v[86:89], v[158:161], v[182:185], v[86:89]
	v_mfma_f32_16x16x32_bf16 v[86:89], v[162:165], v[186:189], v[86:89]
	v_mfma_f32_16x16x32_bf16 v[74:77], v[150:153], v[190:193], v[74:77]
	v_mfma_f32_16x16x32_bf16 v[74:77], v[154:157], v[194:197], v[74:77]
	v_mfma_f32_16x16x32_bf16 v[70:73], v[158:161], v[190:193], v[70:73]
	v_mfma_f32_16x16x32_bf16 v[70:73], v[162:165], v[194:197], v[70:73]
	s_barrier
	s_setprio 0
	s_add_i32 s42, s78, s52
	v_lshl_add_u64 v[40:41], v[198:199], 0, s[18:19]
	s_mov_b32 m0, s42
	ds_read_b128 v[166:169], v244 offset:49152
	ds_read_b128 v[170:173], v244 offset:50176
	ds_read_b128 v[174:177], v244 offset:51200
	ds_read_b128 v[178:181], v244 offset:52224
	ds_read_b128 v[182:185], v244 offset:53248
	ds_read_b128 v[186:189], v244 offset:54272
	ds_read_b128 v[190:193], v244 offset:55296
	ds_read_b128 v[194:197], v244 offset:56320
	global_load_lds_dwordx4 v[40:41], off
	s_add_i32 m0, s42, 0x2000
	s_add_u32 s40, s40, 0x80080
	v_lshl_add_u64 v[40:41], v[200:201], 0, s[18:19]
	s_addc_u32 s41, s41, 0
	s_add_i32 s42, s79, s52
	global_load_lds_dwordx4 v[40:41], off
	v_lshl_add_u64 v[40:41], s[40:41], 0, v[210:211]
	s_mov_b32 m0, s42
	s_nop 0
	global_load_lds_dwordx4 v[40:41], off
	v_lshl_add_u64 v[40:41], s[40:41], 0, v[214:215]
	s_add_i32 m0, s42, 0x2000
	s_nop 0
	global_load_lds_dwordx4 v[40:41], off
	v_lshl_add_u64 v[40:41], v[246:247], 0, s[18:19]
	s_mov_b32 m0, s65
	s_nop 0
	global_load_lds_dwordx4 v[40:41], off
	v_lshl_add_u64 v[40:41], v[248:249], 0, s[18:19]
	s_mov_b32 m0, s66
	s_nop 0
	global_load_lds_dwordx4 v[40:41], off
	s_waitcnt vmcnt(8)
	s_waitcnt lgkmcnt(0)
	s_setprio 1
	s_barrier
	v_mfma_f32_16x16x32_bf16 v[66:69], v[134:137], v[166:169], v[66:69]
	v_mfma_f32_16x16x32_bf16 v[66:69], v[138:141], v[170:173], v[66:69]
	v_mfma_f32_16x16x32_bf16 v[62:65], v[142:145], v[166:169], v[62:65]
	v_mfma_f32_16x16x32_bf16 v[62:65], v[146:149], v[170:173], v[62:65]
	v_mfma_f32_16x16x32_bf16 v[50:53], v[134:137], v[174:177], v[50:53]
	v_mfma_f32_16x16x32_bf16 v[50:53], v[138:141], v[178:181], v[50:53]
	v_mfma_f32_16x16x32_bf16 v[46:49], v[142:145], v[174:177], v[46:49]
	v_mfma_f32_16x16x32_bf16 v[46:49], v[146:149], v[178:181], v[46:49]
	v_mfma_f32_16x16x32_bf16 v[30:33], v[134:137], v[182:185], v[30:33]
	v_mfma_f32_16x16x32_bf16 v[30:33], v[138:141], v[186:189], v[30:33]
	v_mfma_f32_16x16x32_bf16 v[26:29], v[142:145], v[182:185], v[26:29]
	v_mfma_f32_16x16x32_bf16 v[26:29], v[146:149], v[186:189], v[26:29]
	v_mfma_f32_16x16x32_bf16 v[14:17], v[134:137], v[190:193], v[14:17]
	v_mfma_f32_16x16x32_bf16 v[14:17], v[138:141], v[194:197], v[14:17]
	v_mfma_f32_16x16x32_bf16 v[10:13], v[142:145], v[190:193], v[10:13]
	v_mfma_f32_16x16x32_bf16 v[10:13], v[146:149], v[194:197], v[10:13]
	v_mfma_f32_16x16x32_bf16 v[58:61], v[150:153], v[166:169], v[58:61]
	v_mfma_f32_16x16x32_bf16 v[58:61], v[154:157], v[170:173], v[58:61]
	v_mfma_f32_16x16x32_bf16 v[54:57], v[158:161], v[166:169], v[54:57]
	v_mfma_f32_16x16x32_bf16 v[54:57], v[162:165], v[170:173], v[54:57]
	v_mfma_f32_16x16x32_bf16 v[40:43], v[150:153], v[174:177], v[42:45]
	v_mfma_f32_16x16x32_bf16 v[42:45], v[154:157], v[178:181], v[40:43]
	v_mfma_f32_16x16x32_bf16 v[36:39], v[158:161], v[174:177], v[36:39]
	v_mfma_f32_16x16x32_bf16 v[38:41], v[162:165], v[178:181], v[36:39]
	v_mfma_f32_16x16x32_bf16 v[22:25], v[150:153], v[182:185], v[22:25]
	v_mfma_f32_16x16x32_bf16 v[22:25], v[154:157], v[186:189], v[22:25]
	v_mfma_f32_16x16x32_bf16 v[18:21], v[158:161], v[182:185], v[18:21]
	v_mfma_f32_16x16x32_bf16 v[18:21], v[162:165], v[186:189], v[18:21]
	v_mfma_f32_16x16x32_bf16 v[6:9], v[150:153], v[190:193], v[6:9]
	v_mfma_f32_16x16x32_bf16 v[6:9], v[154:157], v[194:197], v[6:9]
	v_mfma_f32_16x16x32_bf16 v[2:5], v[158:161], v[190:193], v[2:5]
	v_mfma_f32_16x16x32_bf16 v[2:5], v[162:165], v[194:197], v[2:5]
	s_barrier
	s_setprio 0
	s_add_i32 vcc_lo, vcc_lo, 2
	s_add_u32 s36, s36, 0x100
	s_addc_u32 s37, s37, 0
	s_cmp_gt_u32 vcc_lo, 29
	s_cbranch_scc0 .LBB0_1644
	s_branch .LBB0_1648
.Lrss_wout:
	s_add_i32 m0, s54, 0x21200
	s_nop 0
	global_load_lds_dwordx4 v[222:223], off
	s_branch .LBB0_1643
